# nt policy also on the fused-epilogue residual loads and the row-phase split-K partial loads
# baseline (speedup 1.0000x reference)
; __device__ __forceinline__ void panel_rms(const f32x4 (&v)[2][2][4][2], int pm, int pn, int wr, int wc, int fr, int fq, LAS unsigned char* xl, int wid, int lane, float* slots, unsigned* cnt) {
;     ...
;     if (lane == 0) __hip_atomic_fetch_add(cnt + 64 * pm, 1u, __ATOMIC_RELAXED, __HIP_MEMORY_SCOPE_AGENT);
;     if (wid == 0) {
;         unsigned sp = 0;
;         while ((unsigned)__builtin_amdgcn_readfirstlane((int)__hip_atomic_load(cnt + 64 * pm, __ATOMIC_RELAXED, __HIP_MEMORY_SCOPE_AGENT)) < 32u) { __builtin_amdgcn_s_sleep(2); if (++sp > (1u << 21)) break; }
; __device__ __forceinline__ void fused_epi(f32x4 (&acc)[2][2][4][2], const Unit& u, int wr, int wc, int fr, int fq, LAS unsigned char* xl, int wid, int lane, const FuseArgs& f) {
;     ...
;                 for (int bj = 0; bj < 2; ++bj) { const size_t off = (size_t)(pm * BM + r) * DM + colb + bj * HALF;
;                     const u32x4 xw = *(const u32x4*)((const bf16_t*)(f.ws + WS_XR) + off);
.LBB0_84:
	s_or_b64 exec, exec, s[12:13]
	s_lshl_b32 s32, s53, 19
	s_add_u32 s34, s78, s32
	s_addc_u32 s35, s79, 0
	s_lshl_b32 s32, s22, 9
	s_add_u32 s34, s34, s32
	s_addc_u32 s35, s35, 0
	v_lshlrev_b32_e32 v217, 11, v167
	v_lshl_add_u32 v217, v213, 1, v217
	global_load_dwordx4 v[224:227], v217, s[34:35] nt
	global_load_dwordx4 v[228:231], v217, s[34:35] offset:256 nt
	v_lshlrev_b32_e32 v217, 11, v198
	v_lshl_add_u32 v217, v213, 1, v217
	global_load_dwordx4 v[232:235], v217, s[34:35] nt
	global_load_dwordx4 v[236:239], v217, s[34:35] offset:256 nt
	v_lshlrev_b32_e32 v217, 11, v200
	v_lshl_add_u32 v217, v213, 1, v217
	global_load_dwordx4 v[240:243], v217, s[34:35] nt
	global_load_dwordx4 v[244:247], v217, s[34:35] offset:256 nt
	v_lshlrev_b32_e32 v217, 11, v202
	v_lshl_add_u32 v217, v213, 1, v217
	global_load_dwordx4 v[248:251], v217, s[34:35] nt
	v_readlane_b32 s12, v255, 31
	v_readlane_b32 s13, v255, 32
	s_andn2_b64 vcc, exec, s[12:13]
	s_cbranch_vccnz .LBB0_98
	s_lshl_b32 s12, s53, 6
	s_ashr_i32 s13, s12, 31
	s_lshl_b64 s[12:13], s[12:13], 2
	s_add_u32 s12, s39, s12
	s_addc_u32 s13, s47, s13
	s_mov_b32 s21, 0x200001
	s_branch .LBB0_87

; __device__ __forceinline__ unsigned cvt_pk_bf16(float lo, float hi) { const f32x2 v = (f32x2){lo, hi}; return __builtin_bit_cast(unsigned, __builtin_convertvector(v, bf16v2)); }
; __device__ __forceinline__ f32x4 bfx4_lo(u32x4 w) { return (f32x4){bf_lo(w.x), bf_hi(w.x), bf_lo(w.y), bf_hi(w.y)}; }
; __device__ __forceinline__ f32x4 bfx4_hi(u32x4 w) { return (f32x4){bf_lo(w.z), bf_hi(w.z), bf_lo(w.w), bf_hi(w.w)}; }
; __device__ __forceinline__ void fused_epi(f32x4 (&acc)[2][2][4][2], const Unit& u, int wr, int wc, int fr, int fq, LAS unsigned char* xl, int wid, int lane, const FuseArgs& f) {
;     ...
;             for (int m = 0; m < 4; ++m) { const int r = ai * HALF + wr * 64 + m * 16 + fr; const float rstd = S[r];
; #pragma unroll
;                 for (int bj = 0; bj < 2; ++bj) { const size_t off = (size_t)(pm * BM + r) * DM + colb + bj * HALF;
;                     const u32x4 xw = *(const u32x4*)((const bf16_t*)(f.ws + WS_XR) + off);
;                     const f32x4 x0 = bfx4_lo(xw) + Gv[bj][0] * (acc[ai][bj][m][0] * rstd), x1 = bfx4_hi(xw) + Gv[bj][1] * (acc[ai][bj][m][1] * rstd);
;                     if (f.out_f32) { *(f32x4*)(f.xoutf + off) = x0; *(f32x4*)(f.xoutf + off + 4) = x1; acc[ai][bj][m][0] = x0; acc[ai][bj][m][1] = x1; }
;                     else { u32x4 w; w.x = cvt_pk_bf16(x0[0], x0[1]); w.y = cvt_pk_bf16(x0[2], x0[3]); w.z = cvt_pk_bf16(x1[0], x1[1]); w.w = cvt_pk_bf16(x1[2], x1[3]);
;                         *(u32x4*)((bf16_t*)(f.ws + WS_XR) + off) = w; acc[ai][bj][m][0] = bfx4_lo(w); acc[ai][bj][m][1] = bfx4_hi(w); } }
.LBB0_108:
	v_lshlrev_b32_e32 v217, 11, v202
	v_lshl_add_u32 v217, v213, 1, v217
	global_load_dwordx4 v[120:123], v217, s[34:35] offset:256 nt
	v_lshlrev_b32_e32 v217, 11, v204
	v_lshl_add_u32 v217, v213, 1, v217
	global_load_dwordx4 v[124:127], v217, s[34:35] nt
	global_load_dwordx4 v[96:99], v217, s[34:35] offset:256 nt
	v_lshlrev_b32_e32 v217, 11, v206
	v_lshl_add_u32 v217, v213, 1, v217
	global_load_dwordx4 v[104:107], v217, s[34:35] nt
	s_nop 1
	v_add_u32_e32 v128, s9, v198
	v_ashrrev_i32_e32 v129, 31, v128
	v_lshlrev_b64 v[128:129], 10, v[128:129]
	v_lshl_add_u64 v[148:149], v[128:129], 0, v[176:177]
	v_lshl_add_u64 v[150:151], v[148:149], 1, s[78:79]
	ds_read_b32 v144, v199
	s_mov_b64 s[68:69], -1
	s_and_b64 vcc, exec, s[12:13]
	s_waitcnt lgkmcnt(0)
	v_pk_mul_f32 v[134:135], v[118:119], v[144:145] op_sel_hi:[1,0]
	v_pk_mul_f32 v[146:147], v[116:117], v[144:145] op_sel_hi:[1,0]
	v_pk_mul_f32 v[160:161], v[112:113], v[144:145] op_sel_hi:[1,0]
	s_nop 1
	v_mov_b32_e32 v130, v232
	v_mov_b32_e32 v131, v233
	v_mov_b32_e32 v132, v234
	v_mov_b32_e32 v133, v235
	v_lshlrev_b32_e32 v128, 16, v130
	v_and_b32_e32 v129, 0xffff0000, v130
	v_lshlrev_b32_e32 v130, 16, v131
	v_and_b32_e32 v131, 0xffff0000, v131
	v_pk_fma_f32 v[130:131], v[182:183], v[134:135], v[130:131]
	v_pk_fma_f32 v[128:129], v[184:185], v[146:147], v[128:129]
	v_lshlrev_b32_e32 v146, 16, v132
	v_and_b32_e32 v147, 0xffff0000, v132
	v_lshlrev_b32_e32 v132, 16, v133
	v_and_b32_e32 v133, 0xffff0000, v133
	v_pk_mul_f32 v[134:135], v[114:115], v[144:145] op_sel_hi:[1,0]
	s_nop 0
	v_pk_fma_f32 v[134:135], v[178:179], v[134:135], v[132:133]
	v_pk_fma_f32 v[132:133], v[180:181], v[160:161], v[146:147]
	v_lshl_add_u64 v[146:147], v[148:149], 2, s[42:43]
	s_cbranch_vccnz .LBB0_110
	s_mov_b64 s[68:69], 0
	global_store_dwordx4 v[146:147], v[128:131], off
	global_store_dwordx4 v[146:147], v[132:135], off offset:16

; __device__ __forceinline__ unsigned cvt_pk_bf16(float lo, float hi) { const f32x2 v = (f32x2){lo, hi}; return __builtin_bit_cast(unsigned, __builtin_convertvector(v, bf16v2)); }
; __device__ __forceinline__ f32x4 bfx4_lo(u32x4 w) { return (f32x4){bf_lo(w.x), bf_hi(w.x), bf_lo(w.y), bf_hi(w.y)}; }
; __device__ __forceinline__ f32x4 bfx4_hi(u32x4 w) { return (f32x4){bf_lo(w.z), bf_hi(w.z), bf_lo(w.w), bf_hi(w.w)}; }
; __device__ __forceinline__ void fused_epi(f32x4 (&acc)[2][2][4][2], const Unit& u, int wr, int wc, int fr, int fq, LAS unsigned char* xl, int wid, int lane, const FuseArgs& f) {
;     ...
;             for (int m = 0; m < 4; ++m) { const int r = ai * HALF + wr * 64 + m * 16 + fr; const float rstd = S[r];
; #pragma unroll
;                 for (int bj = 0; bj < 2; ++bj) { const size_t off = (size_t)(pm * BM + r) * DM + colb + bj * HALF;
;                     const u32x4 xw = *(const u32x4*)((const bf16_t*)(f.ws + WS_XR) + off);
;                     const f32x4 x0 = bfx4_lo(xw) + Gv[bj][0] * (acc[ai][bj][m][0] * rstd), x1 = bfx4_hi(xw) + Gv[bj][1] * (acc[ai][bj][m][1] * rstd);
;                     if (f.out_f32) { *(f32x4*)(f.xoutf + off) = x0; *(f32x4*)(f.xoutf + off + 4) = x1; acc[ai][bj][m][0] = x0; acc[ai][bj][m][1] = x1; }
;                     else { u32x4 w; w.x = cvt_pk_bf16(x0[0], x0[1]); w.y = cvt_pk_bf16(x0[2], x0[3]); w.z = cvt_pk_bf16(x1[0], x1[1]); w.w = cvt_pk_bf16(x1[2], x1[3]);
;                         *(u32x4*)((bf16_t*)(f.ws + WS_XR) + off) = w; acc[ai][bj][m][0] = bfx4_lo(w); acc[ai][bj][m][1] = bfx4_hi(w); } }
.LBB0_116:
	v_lshlrev_b32_e32 v217, 11, v206
	v_lshl_add_u32 v217, v213, 1, v217
	global_load_dwordx4 v[112:115], v217, s[34:35] offset:256 nt
	v_lshlrev_b32_e32 v217, 11, v208
	v_lshl_add_u32 v217, v213, 1, v217
	global_load_dwordx4 v[116:119], v217, s[34:35] nt
	global_load_dwordx4 v[88:91], v217, s[34:35] offset:256 nt
	v_lshlrev_b32_e32 v217, 11, v210
	v_lshl_add_u32 v217, v213, 1, v217
	global_load_dwordx4 v[80:83], v217, s[34:35] nt
	s_nop 1
	v_add_u32_e32 v128, s9, v200
	v_ashrrev_i32_e32 v129, 31, v128
	v_lshlrev_b64 v[128:129], 10, v[128:129]
	v_lshl_add_u64 v[148:149], v[128:129], 0, v[176:177]
	v_lshl_add_u64 v[150:151], v[148:149], 1, s[78:79]
	ds_read_b32 v144, v201
	s_mov_b64 s[68:69], -1
	s_and_b64 vcc, exec, s[12:13]
	s_waitcnt lgkmcnt(0)
	v_pk_mul_f32 v[134:135], v[110:111], v[144:145] op_sel_hi:[1,0]
	v_pk_mul_f32 v[146:147], v[108:109], v[144:145] op_sel_hi:[1,0]
	v_pk_mul_f32 v[160:161], v[100:101], v[144:145] op_sel_hi:[1,0]
	s_nop 1
	v_mov_b32_e32 v130, v240
	v_mov_b32_e32 v131, v241
	v_mov_b32_e32 v132, v242
	v_mov_b32_e32 v133, v243
	v_lshlrev_b32_e32 v128, 16, v130
	v_and_b32_e32 v129, 0xffff0000, v130
	v_lshlrev_b32_e32 v130, 16, v131
	v_and_b32_e32 v131, 0xffff0000, v131
	v_pk_fma_f32 v[130:131], v[182:183], v[134:135], v[130:131]
	v_pk_fma_f32 v[128:129], v[184:185], v[146:147], v[128:129]
	v_lshlrev_b32_e32 v146, 16, v132
	v_and_b32_e32 v147, 0xffff0000, v132
	v_lshlrev_b32_e32 v132, 16, v133
	v_and_b32_e32 v133, 0xffff0000, v133
	v_pk_mul_f32 v[134:135], v[102:103], v[144:145] op_sel_hi:[1,0]
	s_nop 0
	v_pk_fma_f32 v[134:135], v[178:179], v[134:135], v[132:133]
	v_pk_fma_f32 v[132:133], v[180:181], v[160:161], v[146:147]
	v_lshl_add_u64 v[146:147], v[148:149], 2, s[42:43]
	s_cbranch_vccnz .LBB0_118
	s_mov_b64 s[68:69], 0
	global_store_dwordx4 v[146:147], v[128:131], off
	global_store_dwordx4 v[146:147], v[132:135], off offset:16

; __device__ __forceinline__ unsigned cvt_pk_bf16(float lo, float hi) { const f32x2 v = (f32x2){lo, hi}; return __builtin_bit_cast(unsigned, __builtin_convertvector(v, bf16v2)); }
; __device__ __forceinline__ f32x4 bfx4_lo(u32x4 w) { return (f32x4){bf_lo(w.x), bf_hi(w.x), bf_lo(w.y), bf_hi(w.y)}; }
; __device__ __forceinline__ f32x4 bfx4_hi(u32x4 w) { return (f32x4){bf_lo(w.z), bf_hi(w.z), bf_lo(w.w), bf_hi(w.w)}; }
; __device__ __forceinline__ void fused_epi(f32x4 (&acc)[2][2][4][2], const Unit& u, int wr, int wc, int fr, int fq, LAS unsigned char* xl, int wid, int lane, const FuseArgs& f) {
;     ...
;             for (int m = 0; m < 4; ++m) { const int r = ai * HALF + wr * 64 + m * 16 + fr; const float rstd = S[r];
; #pragma unroll
;                 for (int bj = 0; bj < 2; ++bj) { const size_t off = (size_t)(pm * BM + r) * DM + colb + bj * HALF;
;                     const u32x4 xw = *(const u32x4*)((const bf16_t*)(f.ws + WS_XR) + off);
;                     const f32x4 x0 = bfx4_lo(xw) + Gv[bj][0] * (acc[ai][bj][m][0] * rstd), x1 = bfx4_hi(xw) + Gv[bj][1] * (acc[ai][bj][m][1] * rstd);
;                     if (f.out_f32) { *(f32x4*)(f.xoutf + off) = x0; *(f32x4*)(f.xoutf + off + 4) = x1; acc[ai][bj][m][0] = x0; acc[ai][bj][m][1] = x1; }
;                     else { u32x4 w; w.x = cvt_pk_bf16(x0[0], x0[1]); w.y = cvt_pk_bf16(x0[2], x0[3]); w.z = cvt_pk_bf16(x1[0], x1[1]); w.w = cvt_pk_bf16(x1[2], x1[3]);
;                         *(u32x4*)((bf16_t*)(f.ws + WS_XR) + off) = w; acc[ai][bj][m][0] = bfx4_lo(w); acc[ai][bj][m][1] = bfx4_hi(w); } }
.LBB0_124:
	v_lshlrev_b32_e32 v217, 11, v210
	v_lshl_add_u32 v217, v213, 1, v217
	global_load_dwordx4 v[108:111], v217, s[34:35] offset:256 nt
	s_nop 1
	v_add_u32_e32 v128, s9, v202
	v_ashrrev_i32_e32 v129, 31, v128
	v_lshlrev_b64 v[128:129], 10, v[128:129]
	v_lshl_add_u64 v[148:149], v[128:129], 0, v[176:177]
	v_lshl_add_u64 v[150:151], v[148:149], 1, s[78:79]
	ds_read_b32 v144, v203
	s_mov_b64 s[68:69], -1
	s_and_b64 vcc, exec, s[12:13]
	s_waitcnt lgkmcnt(0)
	v_pk_mul_f32 v[134:135], v[94:95], v[144:145] op_sel_hi:[1,0]
	v_pk_mul_f32 v[146:147], v[92:93], v[144:145] op_sel_hi:[1,0]
	v_pk_mul_f32 v[160:161], v[84:85], v[144:145] op_sel_hi:[1,0]
	s_nop 1
	v_mov_b32_e32 v130, v248
	v_mov_b32_e32 v131, v249
	v_mov_b32_e32 v132, v250
	v_mov_b32_e32 v133, v251
	v_lshlrev_b32_e32 v128, 16, v130
	v_and_b32_e32 v129, 0xffff0000, v130
	v_lshlrev_b32_e32 v130, 16, v131
	v_and_b32_e32 v131, 0xffff0000, v131
	v_pk_fma_f32 v[130:131], v[182:183], v[134:135], v[130:131]
	v_pk_fma_f32 v[128:129], v[184:185], v[146:147], v[128:129]
	v_lshlrev_b32_e32 v146, 16, v132
	v_and_b32_e32 v147, 0xffff0000, v132
	v_lshlrev_b32_e32 v132, 16, v133
	v_and_b32_e32 v133, 0xffff0000, v133
	v_pk_mul_f32 v[134:135], v[86:87], v[144:145] op_sel_hi:[1,0]
	s_nop 0
	v_pk_fma_f32 v[134:135], v[178:179], v[134:135], v[132:133]
	v_pk_fma_f32 v[132:133], v[180:181], v[160:161], v[146:147]
	v_lshl_add_u64 v[146:147], v[148:149], 2, s[42:43]
	s_cbranch_vccnz .LBB0_126
	s_mov_b64 s[68:69], 0
	global_store_dwordx4 v[146:147], v[128:131], off
	global_store_dwordx4 v[146:147], v[132:135], off offset:16

; __device__ __forceinline__ f32x4 bfx4_lo(u32x4 w) { return (f32x4){bf_lo(w.x), bf_hi(w.x), bf_lo(w.y), bf_hi(w.y)}; }
; __device__ __forceinline__ void phase_rows(const Params& p, const RowArgs& a, int G, int wave, int lane) {
;     ...
;         if (bmaj) mp = (it < ppw) ? (gw / wpb) * (SEQ / 2) + (gw % wpb) + it * wpb : ML / 2 + gw + (it - ppw) * NGW;
;         else mp = ((a.ctx_only && !bmaj) ? ML / 2 : 0) + gw + it * NGW;
;         if (mp >= a.nrows / 2) break;
;         const int m0 = 2 * mp; const bool isl = m0 < ML; const int rb = isl ? (m0 >> 12) : 8;
;         const bool use_y = a.has_y && !(a.lat_no_y && isl);
;         const size_t xoff = isl ? (size_t)m0 * DM : (size_t)(m0 - ML) * DM;
;         const void* xrb = isl ? a.xlat : a.xctx; void* xob = isl ? a.olat : a.octx;
;         bf16_t* xn = XN + (size_t)m0 * DM;
;         const size_t moff = (size_t)rb * NMOD;
;         f32x4 v[2][4], y[2][4];
;         if (a.xin_f32) {
; #pragma unroll
;             for (int u = 0; u < 2; ++u)
; #pragma unroll
;                 for (int j = 0; j < 4; ++j) v[u][j] = *(const f32x4*)((const float*)xrb + xoff + u * DM + 8 * lane + 512 * (j >> 1) + 4 * (j & 1));
;         } else {
; #pragma unroll
;             for (int u = 0; u < 2; ++u)
; #pragma unroll
;                 for (int jb = 0; jb < 2; ++jb) { const u32x4 xw = *(const u32x4*)((const bf16_t*)xrb + xoff + u * DM + 8 * lane + 512 * jb); v[u][2 * jb] = bfx4_lo(xw); v[u][2 * jb + 1] = bfx4_hi(xw); }
;         }
;         if (use_y) {
;             if (isl || !a.ctx_split) {
; #pragma unroll
;                 for (int u = 0; u < 2; ++u)
; #pragma unroll
;                     for (int jb = 0; jb < 2; ++jb) { const u32x4 yw = *(const u32x4*)(xn + u * DM + 8 * lane + 512 * jb); y[u][2 * jb] = bfx4_lo(yw); y[u][2 * jb + 1] = bfx4_hi(yw); }
;             } else {
;                 const float* part = (const float*)p.out;
; #pragma unroll
;                 for (int u = 0; u < 2; ++u)
; #pragma unroll
;                     for (int j = 0; j < 4; ++j) { const float* pp = part + (size_t)(m0 + u - ML) * DM + 8 * lane + 512 * (j >> 1) + 4 * (j & 1); f32x4 s = *(const f32x4*)pp;
; #pragma unroll
;                         for (int k = 1; k < pg8::KSPLIT; ++k) s += *(const f32x4*)(pp + (size_t)k * MC * DM);
;                         y[u][j] = s; }
.LBB0_210:
	s_cmp_ge_i32 s11, s19
	s_mov_b64 s[0:1], -1
	s_cbranch_scc1 .LBB0_204
	s_lshl_b32 s4, s11, 1
	s_cmpk_lt_i32 s11, 0x4000
	s_cselect_b64 s[0:1], -1, 0
	s_ashr_i32 s5, s4, 31
	s_add_i32 s30, s4, 0xffff8000
	s_cmpk_gt_i32 s11, 0x3fff
	s_cselect_b64 s[8:9], -1, 0
	s_and_b64 s[6:7], s[8:9], exec
	s_cselect_b32 s7, 0, s5
	s_cselect_b32 s6, s30, s4
	s_cselect_b32 s23, s99, s79
	s_cselect_b32 s26, s98, s78
	s_lshl_b64 s[24:25], s[6:7], 11
	s_add_u32 s24, s26, s24
	s_addc_u32 s25, s23, s25
	global_load_dwordx4 v[116:119], v170, s[24:25] nt
	global_load_dwordx4 v[112:115], v170, s[24:25] offset:1024 nt
	global_load_dwordx4 v[108:111], v170, s[24:25] offset:2048 nt
	global_load_dwordx4 v[104:107], v170, s[24:25] offset:3072 nt
	v_lshl_add_u64 v[248:249], s[24:25], 0, v[250:251]
	s_add_i32 s32, s11, s52
	s_cmpk_lt_i32 s32, 0x4000
	s_cselect_b32 s32, 1, 0
	s_and_b32 s32, s32, s82
	s_and_b64 vcc, exec, s[0:1]
	s_cbranch_vccnz .LBB0_213
	s_lshl_b64 s[24:25], s[30:31], 12
	v_lshl_add_u64 v[88:89], v[176:177], 0, s[24:25]
	v_add_co_u32_e32 v96, vcc, 0x800000, v88
	global_load_dwordx4 v[84:87], v[88:89], off offset:16 nt
	global_load_dwordx4 v[80:83], v[88:89], off nt
	s_mov_b64 s[26:27], 0x800000
	v_addc_co_u32_e32 v97, vcc, 0, v89, vcc
	v_lshl_add_u64 v[94:95], v[88:89], 0, s[26:27]
	global_load_dwordx4 v[90:93], v[96:97], off nt
	global_load_dwordx4 v[126:129], v[94:95], off offset:16 nt
	s_mov_b64 s[28:29], 0x1000000
	v_add_co_u32_e32 v122, vcc, 0x1000000, v88
	s_mov_b64 s[62:63], 0x1800000
	s_nop 0
	v_addc_co_u32_e32 v123, vcc, 0, v89, vcc
	v_add_co_u32_e32 v120, vcc, 0x1800000, v88
	v_lshl_add_u64 v[100:101], v[88:89], 0, s[62:63]
	s_nop 0
	v_addc_co_u32_e32 v121, vcc, 0, v89, vcc
	v_add_co_u32_e32 v102, vcc, 0x2000000, v88
	s_mov_b64 s[64:65], 0x2000000
	s_nop 0
	v_addc_co_u32_e32 v103, vcc, 0, v89, vcc
	v_add_co_u32_e32 v124, vcc, 0x2800000, v88
	s_mov_b64 s[68:69], 0x2800000
	s_nop 0
	v_addc_co_u32_e32 v125, vcc, 0, v89, vcc
	s_mov_b64 s[70:71], 0x3000000
	v_lshl_add_u64 v[142:143], v[88:89], 0, s[70:71]
	s_mov_b64 s[74:75], 0x3800000
	v_lshl_add_u64 v[146:147], v[88:89], 0, s[74:75]
	s_mov_b64 s[76:77], 0x800800
	s_mov_b64 s[40:41], s[34:35]
	s_mov_b64 s[34:35], 0x1000800
	s_mov_b64 s[86:87], 0x1800800
	s_mov_b64 s[94:95], 0x2000800
	s_mov_b64 s[14:15], 0x2800800
	s_mov_b32 s33, s96
	s_mov_b32 s39, s97
	s_mov_b64 s[96:97], 0x3000800
	s_mov_b64 s[36:37], 0x3800800
	s_add_i32 s30, s4, 0xffff8001
	s_lshl_b64 s[24:25], s[30:31], 12
	s_mov_b32 s23, 0x1000000
	s_waitcnt vmcnt(0)
	v_pk_add_f32 v[98:99], v[82:83], v[92:93]
	v_lshl_add_u64 v[92:93], v[88:89], 0, s[28:29]
	v_pk_add_f32 v[90:91], v[80:81], v[90:91]
	global_load_dwordx4 v[80:83], v[122:123], off nt
	s_nop 0
	global_load_dwordx4 v[92:95], v[92:93], off offset:16 nt
	v_pk_add_f32 v[86:87], v[86:87], v[128:129]
	v_pk_add_f32 v[84:85], v[84:85], v[126:127]
	s_waitcnt vmcnt(1)
	v_pk_add_f32 v[98:99], v[98:99], v[82:83]
	v_pk_add_f32 v[90:91], v[90:91], v[80:81]
	global_load_dwordx4 v[80:83], v[120:121], off nt
	global_load_dwordx4 v[130:133], v[100:101], off offset:16 nt
	v_lshl_add_u64 v[100:101], v[88:89], 0, s[64:65]
	s_waitcnt vmcnt(2)
	v_pk_add_f32 v[86:87], v[86:87], v[94:95]
	v_pk_add_f32 v[84:85], v[84:85], v[92:93]
	s_waitcnt vmcnt(1)
	v_pk_add_f32 v[98:99], v[98:99], v[82:83]
	v_pk_add_f32 v[90:91], v[90:91], v[80:81]
	global_load_dwordx4 v[80:83], v[102:103], off nt
	global_load_dwordx4 v[134:137], v[100:101], off offset:16 nt
	v_lshl_add_u64 v[100:101], v[88:89], 0, s[68:69]
	s_waitcnt vmcnt(2)
	v_pk_add_f32 v[86:87], v[86:87], v[132:133]
	v_pk_add_f32 v[84:85], v[84:85], v[130:131]
	s_waitcnt vmcnt(1)
	v_pk_add_f32 v[98:99], v[98:99], v[82:83]
	v_pk_add_f32 v[90:91], v[90:91], v[80:81]
	global_load_dwordx4 v[80:83], v[124:125], off nt
	global_load_dwordx4 v[138:141], v[100:101], off offset:16 nt
	v_add_co_u32_e32 v100, vcc, 0x3000000, v88
	s_waitcnt vmcnt(2)
	v_pk_add_f32 v[86:87], v[86:87], v[136:137]
	v_addc_co_u32_e32 v101, vcc, 0, v89, vcc
	v_pk_add_f32 v[84:85], v[84:85], v[134:135]
	s_waitcnt vmcnt(1)
	v_pk_add_f32 v[98:99], v[98:99], v[82:83]
	v_pk_add_f32 v[90:91], v[90:91], v[80:81]
	global_load_dwordx4 v[80:83], v[100:101], off nt
	s_nop 0
	global_load_dwordx4 v[142:145], v[142:143], off offset:16 nt
	s_waitcnt vmcnt(2)
	v_pk_add_f32 v[84:85], v[84:85], v[138:139]
	v_pk_add_f32 v[86:87], v[86:87], v[140:141]
	s_waitcnt vmcnt(1)
	v_pk_add_f32 v[150:151], v[90:91], v[80:81]
	v_add_co_u32_e32 v90, vcc, 0x3800000, v88
	v_pk_add_f32 v[98:99], v[98:99], v[82:83]
	s_nop 0
	v_addc_co_u32_e32 v91, vcc, 0, v89, vcc
	global_load_dwordx4 v[80:83], v[90:91], off nt
	s_nop 0
	global_load_dwordx4 v[146:149], v[146:147], off offset:16 nt
	s_nop 0
	global_load_dwordx4 v[92:95], v[88:89], off offset:2064 nt
	global_load_dwordx4 v[126:129], v[88:89], off offset:2048 nt
	s_waitcnt vmcnt(4)
	v_pk_add_f32 v[84:85], v[84:85], v[142:143]
	v_pk_add_f32 v[86:87], v[86:87], v[144:145]
	s_waitcnt vmcnt(3)
	v_pk_add_f32 v[82:83], v[98:99], v[82:83]
	v_lshl_add_u64 v[98:99], v[88:89], 0, s[76:77]
	global_load_dwordx4 v[130:133], v[96:97], off offset:2048 nt
	s_nop 0
	global_load_dwordx4 v[96:99], v[98:99], off offset:16 nt
	s_waitcnt vmcnt(4)
	v_pk_add_f32 v[86:87], v[86:87], v[148:149]
	v_pk_add_f32 v[84:85], v[84:85], v[146:147]
	v_pk_add_f32 v[80:81], v[150:151], v[80:81]
	s_waitcnt vmcnt(1)
	v_pk_add_f32 v[136:137], v[126:127], v[130:131]
	v_lshl_add_u64 v[130:131], v[88:89], 0, s[34:35]
	v_pk_add_f32 v[134:135], v[128:129], v[132:133]
	global_load_dwordx4 v[126:129], v[122:123], off offset:2048 nt
	s_nop 0
	global_load_dwordx4 v[130:133], v[130:131], off offset:16 nt
	s_waitcnt vmcnt(2)
; __device__ __forceinline__ void phase_rows(const Params& p, const RowArgs& a, int G, int wave, int lane) {
;     ...
;                     for (int j = 0; j < 4; ++j) { const float* pp = part + (size_t)(m0 + u - ML) * DM + 8 * lane + 512 * (j >> 1) + 4 * (j & 1); f32x4 s = *(const f32x4*)pp;
; #pragma unroll
;                         for (int k = 1; k < pg8::KSPLIT; ++k) s += *(const f32x4*)(pp + (size_t)k * MC * DM);
;                         y[u][j] = s; }
	v_pk_add_f32 v[92:93], v[92:93], v[96:97]
	v_pk_add_f32 v[94:95], v[94:95], v[98:99]
	s_waitcnt vmcnt(1)
	v_pk_add_f32 v[136:137], v[136:137], v[126:127]
	v_lshl_add_u64 v[126:127], v[88:89], 0, s[86:87]
	v_pk_add_f32 v[134:135], v[134:135], v[128:129]
	global_load_dwordx4 v[120:123], v[120:121], off offset:2048 nt
	s_nop 0
	global_load_dwordx4 v[126:129], v[126:127], off offset:16 nt
	s_waitcnt vmcnt(2)
	v_pk_add_f32 v[92:93], v[92:93], v[130:131]
	v_pk_add_f32 v[94:95], v[94:95], v[132:133]
	s_waitcnt vmcnt(1)
	v_pk_add_f32 v[138:139], v[134:135], v[122:123]
	v_lshl_add_u64 v[134:135], v[88:89], 0, s[94:95]
	v_pk_add_f32 v[140:141], v[136:137], v[120:121]
	global_load_dwordx4 v[120:123], v[102:103], off offset:2048 nt
	s_nop 0
	global_load_dwordx4 v[134:137], v[134:135], off offset:16 nt
	s_waitcnt vmcnt(2)
	v_pk_add_f32 v[92:93], v[92:93], v[126:127]
	v_pk_add_f32 v[94:95], v[94:95], v[128:129]
	s_waitcnt vmcnt(1)
	v_pk_add_f32 v[102:103], v[138:139], v[122:123]
	v_lshl_add_u64 v[138:139], v[88:89], 0, s[14:15]
	v_pk_add_f32 v[142:143], v[140:141], v[120:121]
	global_load_dwordx4 v[120:123], v[124:125], off offset:2048 nt
	s_nop 0
	global_load_dwordx4 v[138:141], v[138:139], off offset:16 nt
	s_waitcnt vmcnt(2)
	v_pk_add_f32 v[92:93], v[92:93], v[134:135]
	v_pk_add_f32 v[94:95], v[94:95], v[136:137]
	s_waitcnt vmcnt(1)
	v_pk_add_f32 v[142:143], v[142:143], v[120:121]
	v_lshl_add_u64 v[120:121], v[88:89], 0, s[96:97]
	v_pk_add_f32 v[124:125], v[102:103], v[122:123]
	global_load_dwordx4 v[100:103], v[100:101], off offset:2048 nt
	s_nop 0
	global_load_dwordx4 v[120:123], v[120:121], off offset:16 nt
	s_waitcnt vmcnt(2)
	v_pk_add_f32 v[92:93], v[92:93], v[138:139]
	v_pk_add_f32 v[94:95], v[94:95], v[140:141]
	s_waitcnt vmcnt(1)
	v_pk_add_f32 v[142:143], v[142:143], v[100:101]
	v_lshl_add_u64 v[100:101], v[88:89], 0, s[36:37]
	v_pk_add_f32 v[124:125], v[124:125], v[102:103]
	global_load_dwordx4 v[88:91], v[90:91], off offset:2048 nt
	s_nop 0
	global_load_dwordx4 v[100:103], v[100:101], off offset:16 nt
	s_waitcnt vmcnt(2)
	v_pk_add_f32 v[92:93], v[92:93], v[120:121]
	v_lshl_add_u64 v[120:121], v[176:177], 0, s[24:25]
	v_pk_add_f32 v[94:95], v[94:95], v[122:123]
	v_add_co_u32_e32 v128, vcc, s55, v120
	v_lshl_add_u64 v[126:127], v[120:121], 0, s[26:27]
	s_nop 0
	v_addc_co_u32_e32 v129, vcc, 0, v121, vcc
	v_add_co_u32_e32 v132, vcc, s23, v120
	s_mov_b32 s23, 0x1800000
	s_nop 0
	v_addc_co_u32_e32 v133, vcc, 0, v121, vcc
	v_add_co_u32_e32 v136, vcc, s23, v120
	v_lshl_add_u64 v[134:135], v[120:121], 0, s[62:63]
	s_nop 0
	v_addc_co_u32_e32 v137, vcc, 0, v121, vcc
	s_brev_b32 s23, 64
	s_waitcnt vmcnt(1)
	v_pk_add_f32 v[90:91], v[124:125], v[90:91]
	s_waitcnt vmcnt(0)
	v_pk_add_f32 v[94:95], v[94:95], v[102:103]
	v_pk_add_f32 v[92:93], v[92:93], v[100:101]
	global_load_dwordx4 v[100:103], v[120:121], off offset:16 nt
	global_load_dwordx4 v[96:99], v[120:121], off nt
	global_load_dwordx4 v[122:125], v[128:129], off nt
	global_load_dwordx4 v[138:141], v[126:127], off offset:16 nt
	v_pk_add_f32 v[88:89], v[142:143], v[88:89]
	v_lshl_add_u64 v[142:143], v[120:121], 0, s[64:65]
	s_waitcnt vmcnt(1)
	v_pk_add_f32 v[130:131], v[98:99], v[124:125]
	v_lshl_add_u64 v[124:125], v[120:121], 0, s[28:29]
	v_pk_add_f32 v[122:123], v[96:97], v[122:123]
	global_load_dwordx4 v[96:99], v[132:133], off nt
	s_nop 0
	global_load_dwordx4 v[124:127], v[124:125], off offset:16 nt
	s_waitcnt vmcnt(2)
	v_pk_add_f32 v[102:103], v[102:103], v[140:141]
	v_pk_add_f32 v[100:101], v[100:101], v[138:139]
	s_waitcnt vmcnt(1)
	v_pk_add_f32 v[130:131], v[130:131], v[98:99]
	v_pk_add_f32 v[122:123], v[122:123], v[96:97]
	global_load_dwordx4 v[96:99], v[136:137], off nt
	global_load_dwordx4 v[178:181], v[134:135], off offset:16 nt
	s_waitcnt vmcnt(2)
	v_pk_add_f32 v[102:103], v[102:103], v[126:127]
	v_pk_add_f32 v[100:101], v[100:101], v[124:125]
	s_waitcnt vmcnt(1)
	v_pk_add_f32 v[134:135], v[122:123], v[96:97]
	v_add_co_u32_e32 v122, vcc, s23, v120
	v_pk_add_f32 v[130:131], v[130:131], v[98:99]
	s_nop 0
	v_addc_co_u32_e32 v123, vcc, 0, v121, vcc
	global_load_dwordx4 v[96:99], v[122:123], off nt
	global_load_dwordx4 v[182:185], v[142:143], off offset:16 nt
	s_mov_b32 s23, 0x2800000
	v_add_co_u32_e32 v144, vcc, s23, v120
	v_lshl_add_u64 v[142:143], v[120:121], 0, s[68:69]
	s_nop 0
	v_addc_co_u32_e32 v145, vcc, 0, v121, vcc
	s_mov_b32 s23, 0x3000000
	v_add_co_u32_e32 v148, vcc, s23, v120
	s_mov_b32 s23, 0x3800000
	s_nop 0
	v_addc_co_u32_e32 v149, vcc, 0, v121, vcc
	v_add_co_u32_e32 v152, vcc, s23, v120
	s_waitcnt vmcnt(2)
	v_pk_add_f32 v[102:103], v[102:103], v[180:181]
	v_addc_co_u32_e32 v153, vcc, 0, v121, vcc
	v_pk_add_f32 v[100:101], v[100:101], v[178:179]
	s_waitcnt vmcnt(1)
; __device__ __forceinline__ void phase_rows(const Params& p, const RowArgs& a, int G, int wave, int lane) {
;     ...
;                     for (int j = 0; j < 4; ++j) { const float* pp = part + (size_t)(m0 + u - ML) * DM + 8 * lane + 512 * (j >> 1) + 4 * (j & 1); f32x4 s = *(const f32x4*)pp;
; #pragma unroll
;                         for (int k = 1; k < pg8::KSPLIT; ++k) s += *(const f32x4*)(pp + (size_t)k * MC * DM);
;                         y[u][j] = s; }
	v_pk_add_f32 v[130:131], v[130:131], v[98:99]
	v_pk_add_f32 v[134:135], v[134:135], v[96:97]
	global_load_dwordx4 v[96:99], v[144:145], off nt
	global_load_dwordx4 v[186:189], v[142:143], off offset:16 nt
	v_lshl_add_u64 v[142:143], v[120:121], 0, s[70:71]
	s_waitcnt vmcnt(2)
	v_pk_add_f32 v[100:101], v[100:101], v[182:183]
	v_pk_add_f32 v[102:103], v[102:103], v[184:185]
	s_waitcnt vmcnt(1)
	v_pk_add_f32 v[130:131], v[130:131], v[98:99]
	v_pk_add_f32 v[134:135], v[134:135], v[96:97]
	global_load_dwordx4 v[96:99], v[148:149], off nt
	global_load_dwordx4 v[190:193], v[142:143], off offset:16 nt
	v_lshl_add_u64 v[142:143], v[120:121], 0, s[74:75]
	s_waitcnt vmcnt(2)
	v_pk_add_f32 v[102:103], v[102:103], v[188:189]
	v_pk_add_f32 v[100:101], v[100:101], v[186:187]
	s_waitcnt vmcnt(1)
	v_pk_add_f32 v[130:131], v[130:131], v[98:99]
	v_pk_add_f32 v[134:135], v[134:135], v[96:97]
	global_load_dwordx4 v[96:99], v[152:153], off nt
	global_load_dwordx4 v[194:197], v[142:143], off offset:16 nt
	global_load_dwordx4 v[124:127], v[120:121], off offset:2064 nt
	global_load_dwordx4 v[138:141], v[120:121], off offset:2048 nt
	s_waitcnt vmcnt(4)
	v_pk_add_f32 v[102:103], v[102:103], v[192:193]
	v_pk_add_f32 v[100:101], v[100:101], v[190:191]
	s_waitcnt vmcnt(3)
	v_pk_add_f32 v[98:99], v[130:131], v[98:99]
	v_lshl_add_u64 v[130:131], v[120:121], 0, s[76:77]
	global_load_dwordx4 v[178:181], v[128:129], off offset:2048 nt
	s_nop 0
	global_load_dwordx4 v[128:131], v[130:131], off offset:16 nt
	v_pk_add_f32 v[96:97], v[134:135], v[96:97]
	v_lshl_add_u64 v[134:135], v[120:121], 0, s[34:35]
	s_waitcnt vmcnt(4)
	v_pk_add_f32 v[102:103], v[102:103], v[196:197]
	v_pk_add_f32 v[100:101], v[100:101], v[194:195]
	s_mov_b64 s[34:35], s[40:41]
	s_waitcnt vmcnt(1)
	v_pk_add_f32 v[142:143], v[140:141], v[180:181]
	v_pk_add_f32 v[146:147], v[138:139], v[178:179]
	global_load_dwordx4 v[138:141], v[132:133], off offset:2048 nt
	s_nop 0
	global_load_dwordx4 v[132:135], v[134:135], off offset:16 nt
	s_waitcnt vmcnt(2)
	v_pk_add_f32 v[126:127], v[126:127], v[130:131]
	v_pk_add_f32 v[124:125], v[124:125], v[128:129]
	s_waitcnt vmcnt(1)
	v_pk_add_f32 v[146:147], v[146:147], v[138:139]
	v_lshl_add_u64 v[138:139], v[120:121], 0, s[86:87]
	v_pk_add_f32 v[150:151], v[142:143], v[140:141]
	global_load_dwordx4 v[140:143], v[136:137], off offset:2048 nt
	s_nop 0
	global_load_dwordx4 v[136:139], v[138:139], off offset:16 nt
	s_waitcnt vmcnt(2)
	v_pk_add_f32 v[126:127], v[126:127], v[134:135]
	v_pk_add_f32 v[124:125], v[124:125], v[132:133]
	s_mov_b32 s87, s38
	v_readlane_b32 s86, v255, 11
	s_waitcnt vmcnt(1)
	v_pk_add_f32 v[146:147], v[146:147], v[140:141]
	v_lshl_add_u64 v[140:141], v[120:121], 0, s[94:95]
	v_pk_add_f32 v[150:151], v[150:151], v[142:143]
	global_load_dwordx4 v[178:181], v[122:123], off offset:2048 nt
	s_nop 0
	global_load_dwordx4 v[140:143], v[140:141], off offset:16 nt
	s_waitcnt vmcnt(2)
	v_pk_add_f32 v[126:127], v[126:127], v[138:139]
	v_pk_add_f32 v[124:125], v[124:125], v[136:137]
	v_readlane_b32 s94, v255, 27
	v_readlane_b32 s95, v255, 28
	s_waitcnt vmcnt(1)
	v_pk_add_f32 v[122:123], v[150:151], v[180:181]
	v_pk_add_f32 v[150:151], v[146:147], v[178:179]
	v_lshl_add_u64 v[146:147], v[120:121], 0, s[14:15]
	global_load_dwordx4 v[178:181], v[144:145], off offset:2048 nt
	s_nop 0
	global_load_dwordx4 v[144:147], v[146:147], off offset:16 nt
	s_waitcnt vmcnt(2)
	v_pk_add_f32 v[126:127], v[126:127], v[142:143]
	v_pk_add_f32 v[124:125], v[124:125], v[140:141]
	s_waitcnt vmcnt(1)
	v_pk_add_f32 v[154:155], v[150:151], v[178:179]
	v_lshl_add_u64 v[150:151], v[120:121], 0, s[96:97]
	v_pk_add_f32 v[122:123], v[122:123], v[180:181]
	global_load_dwordx4 v[180:183], v[148:149], off offset:2048 nt
	s_nop 0
	global_load_dwordx4 v[148:151], v[150:151], off offset:16 nt
	s_waitcnt vmcnt(2)
	v_pk_add_f32 v[126:127], v[126:127], v[146:147]
	v_pk_add_f32 v[124:125], v[124:125], v[144:145]
	s_mov_b32 s97, s39
	s_mov_b32 s96, s33
	s_waitcnt vmcnt(1)
	v_pk_add_f32 v[180:181], v[154:155], v[180:181]
	v_lshl_add_u64 v[154:155], v[120:121], 0, s[36:37]
	v_pk_add_f32 v[178:179], v[122:123], v[182:183]
	global_load_dwordx4 v[120:123], v[152:153], off offset:2048 nt
	s_nop 0
	global_load_dwordx4 v[152:155], v[154:155], off offset:16 nt
	s_waitcnt vmcnt(2)
	v_pk_add_f32 v[126:127], v[126:127], v[150:151]
	v_pk_add_f32 v[124:125], v[124:125], v[148:149]
	s_waitcnt vmcnt(1)
	v_pk_add_f32 v[122:123], v[178:179], v[122:123]
	v_pk_add_f32 v[120:121], v[180:181], v[120:121]
	s_waitcnt vmcnt(0)
	v_pk_add_f32 v[126:127], v[126:127], v[154:155]
	v_pk_add_f32 v[124:125], v[124:125], v[152:153]

; __device__ __forceinline__ void panel_rms(const f32x4 (&v)[2][2][4][2], int pm, int pn, int wr, int wc, int fr, int fq, LAS unsigned char* xl, int wid, int lane, float* slots, unsigned* cnt) {
;     ...
;     if (lane == 0) __hip_atomic_fetch_add(cnt + 64 * pm, 1u, __ATOMIC_RELAXED, __HIP_MEMORY_SCOPE_AGENT);
;     if (wid == 0) {
;         unsigned sp = 0;
;         while ((unsigned)__builtin_amdgcn_readfirstlane((int)__hip_atomic_load(cnt + 64 * pm, __ATOMIC_RELAXED, __HIP_MEMORY_SCOPE_AGENT)) < 32u) { __builtin_amdgcn_s_sleep(2); if (++sp > (1u << 21)) break; }
; __device__ __forceinline__ void fused_epi(f32x4 (&acc)[2][2][4][2], const Unit& u, int wr, int wc, int fr, int fq, LAS unsigned char* xl, int wid, int lane, const FuseArgs& f) {
;     ...
;                 for (int bj = 0; bj < 2; ++bj) { const size_t off = (size_t)(pm * BM + r) * DM + colb + bj * HALF;
;                     const u32x4 xw = *(const u32x4*)((const bf16_t*)(f.ws + WS_XR) + off);
.LBB0_271:
	s_or_b64 exec, exec, s[68:69]
	s_lshl_b32 s32, s53, 19
	s_add_u32 s34, s78, s32
	s_addc_u32 s35, s79, 0
	s_lshl_b32 s32, s16, 9
	s_add_u32 s34, s34, s32
	s_addc_u32 s35, s35, 0
	v_lshlrev_b32_e32 v217, 11, v167
	v_lshl_add_u32 v217, v191, 1, v217
	global_load_dwordx4 v[224:227], v217, s[34:35] nt
	global_load_dwordx4 v[228:231], v217, s[34:35] offset:256 nt
	v_lshlrev_b32_e32 v217, 11, v176
	v_lshl_add_u32 v217, v191, 1, v217
	global_load_dwordx4 v[232:235], v217, s[34:35] nt
	global_load_dwordx4 v[236:239], v217, s[34:35] offset:256 nt
	v_lshlrev_b32_e32 v217, 11, v178
	v_lshl_add_u32 v217, v191, 1, v217
	global_load_dwordx4 v[240:243], v217, s[34:35] nt
	global_load_dwordx4 v[244:247], v217, s[34:35] offset:256 nt
	v_lshlrev_b32_e32 v217, 11, v180
	v_lshl_add_u32 v217, v191, 1, v217
	global_load_dwordx4 v[248:251], v217, s[34:35] nt
	v_readlane_b32 s26, v255, 21
	v_readlane_b32 s27, v255, 22
	s_andn2_b64 vcc, exec, s[26:27]
	s_cbranch_vccnz .LBB0_285
	s_lshl_b32 s62, s53, 6
	s_ashr_i32 s63, s62, 31
	s_lshl_b64 s[62:63], s[62:63], 2
	s_add_u32 s68, s41, s62
	s_addc_u32 s69, s47, s63
	s_mov_b32 s17, 0x200001
	s_branch .LBB0_274

; __device__ __forceinline__ unsigned cvt_pk_bf16(float lo, float hi) { const f32x2 v = (f32x2){lo, hi}; return __builtin_bit_cast(unsigned, __builtin_convertvector(v, bf16v2)); }
; __device__ __forceinline__ f32x4 bfx4_lo(u32x4 w) { return (f32x4){bf_lo(w.x), bf_hi(w.x), bf_lo(w.y), bf_hi(w.y)}; }
; __device__ __forceinline__ f32x4 bfx4_hi(u32x4 w) { return (f32x4){bf_lo(w.z), bf_hi(w.z), bf_lo(w.w), bf_hi(w.w)}; }
; __device__ __forceinline__ void fused_epi(f32x4 (&acc)[2][2][4][2], const Unit& u, int wr, int wc, int fr, int fq, LAS unsigned char* xl, int wid, int lane, const FuseArgs& f) {
;     ...
;         f32x4 Gv[2][2];
; #pragma unroll
;         for (int bj = 0; bj < 2; ++bj)
; #pragma unroll
;             for (int n = 0; n < 2; ++n) { const int c = colb + bj * HALF + 4 * n; Gv[bj][n] = *(const f32x4*)(f.modl + f.gate_off + mrow + c) * *(const f32x4*)(f.gpost + c); }
; #pragma unroll
;         for (int ai = 0; ai < 2; ++ai)
; #pragma unroll
;             for (int m = 0; m < 4; ++m) { const int r = ai * HALF + wr * 64 + m * 16 + fr; const float rstd = S[r];
; #pragma unroll
;                 for (int bj = 0; bj < 2; ++bj) { const size_t off = (size_t)(pm * BM + r) * DM + colb + bj * HALF;
;                     const u32x4 xw = *(const u32x4*)((const bf16_t*)(f.ws + WS_XR) + off);
;                     const f32x4 x0 = bfx4_lo(xw) + Gv[bj][0] * (acc[ai][bj][m][0] * rstd), x1 = bfx4_hi(xw) + Gv[bj][1] * (acc[ai][bj][m][1] * rstd);
;                     if (f.out_f32) { *(f32x4*)(f.xoutf + off) = x0; *(f32x4*)(f.xoutf + off + 4) = x1; acc[ai][bj][m][0] = x0; acc[ai][bj][m][1] = x1; }
;                     else { u32x4 w; w.x = cvt_pk_bf16(x0[0], x0[1]); w.y = cvt_pk_bf16(x0[2], x0[3]); w.z = cvt_pk_bf16(x1[0], x1[1]); w.w = cvt_pk_bf16(x1[2], x1[3]);
;                         *(u32x4*)((bf16_t*)(f.ws + WS_XR) + off) = w; acc[ai][bj][m][0] = bfx4_lo(w); acc[ai][bj][m][1] = bfx4_hi(w); } }
.LBB0_287:
	s_or_b64 exec, exec, s[68:69]
	s_ashr_i32 s17, s53, 4
	v_lshl_or_b32 v154, s16, 8, v191
	s_mul_hi_i32 s26, s17, 0x6000
	s_mulk_i32 s17, 0x6000
	s_add_u32 s62, s56, s17
	v_ashrrev_i32_e32 v155, 31, v154
	s_addc_u32 s63, s96, s26
	v_lshlrev_b64 v[146:147], 2, v[154:155]
	s_waitcnt vmcnt(0) lgkmcnt(0)
	s_barrier
	v_lshl_add_u64 v[160:161], s[62:63], 0, v[146:147]
	v_lshl_add_u64 v[170:171], s[20:21], 0, v[146:147]
	global_load_dwordx4 v[138:141], v[160:161], off offset:16
	global_load_dwordx4 v[142:145], v[160:161], off
	global_load_dwordx4 v[196:199], v[170:171], off offset:16
	global_load_dwordx4 v[146:149], v[170:171], off
	v_lshlrev_b64 v[154:155], 1, v[154:155]
	s_waitcnt vmcnt(0)
	v_pk_mul_f32 v[150:151], v[144:145], v[148:149]
	v_pk_mul_f32 v[152:153], v[142:143], v[146:147]
	v_pk_mul_f32 v[146:147], v[140:141], v[198:199]
	v_pk_mul_f32 v[148:149], v[138:139], v[196:197]
	global_load_dwordx4 v[138:141], v[160:161], off offset:528
	global_load_dwordx4 v[196:199], v[160:161], off offset:512
	global_load_dwordx4 v[200:203], v[170:171], off offset:528
	global_load_dwordx4 v[204:207], v[170:171], off offset:512
	v_add_u32_e32 v170, s15, v167
	v_ashrrev_i32_e32 v171, 31, v170
	v_lshlrev_b64 v[170:171], 11, v[170:171]
	v_lshl_add_u64 v[170:171], s[78:79], 0, v[170:171]
	v_lshl_add_u64 v[170:171], v[170:171], 0, v[154:155]
	ds_read_b32 v160, v175
	s_waitcnt vmcnt(1)
	v_pk_mul_f32 v[140:141], v[140:141], v[202:203]
	s_waitcnt vmcnt(0)
	v_pk_mul_f32 v[142:143], v[198:199], v[206:207]
	v_pk_mul_f32 v[144:145], v[196:197], v[204:205]
	v_pk_mul_f32 v[138:139], v[138:139], v[200:201]
	s_waitcnt lgkmcnt(0)
	v_pk_mul_f32 v[202:203], v[126:127], v[160:161] op_sel_hi:[1,0]
	v_pk_mul_f32 v[204:205], v[124:125], v[160:161] op_sel_hi:[1,0]
	v_pk_mul_f32 v[206:207], v[120:121], v[160:161] op_sel_hi:[1,0]
	s_waitcnt vmcnt(0)
	s_nop 1
	v_mov_b32_e32 v196, v224
	v_mov_b32_e32 v197, v225
	v_mov_b32_e32 v198, v226
	v_mov_b32_e32 v199, v227
	v_lshlrev_b32_e32 v200, 16, v196
	v_and_b32_e32 v201, 0xffff0000, v196
	v_lshlrev_b32_e32 v196, 16, v197
	v_and_b32_e32 v197, 0xffff0000, v197
	v_pk_fma_f32 v[202:203], v[150:151], v[202:203], v[196:197]
	v_pk_fma_f32 v[196:197], v[152:153], v[204:205], v[200:201]
	v_lshlrev_b32_e32 v200, 16, v198
	v_and_b32_e32 v201, 0xffff0000, v198
	v_lshlrev_b32_e32 v198, 16, v199
	v_and_b32_e32 v199, 0xffff0000, v199
	v_pk_mul_f32 v[204:205], v[122:123], v[160:161] op_sel_hi:[1,0]
	v_cvt_pk_bf16_f32 v196, v196, v197
	v_pk_fma_f32 v[204:205], v[146:147], v[204:205], v[198:199]
	v_pk_fma_f32 v[198:199], v[148:149], v[206:207], v[200:201]
	v_cvt_pk_bf16_f32 v197, v202, v203
	v_cvt_pk_bf16_f32 v198, v198, v199
	v_cvt_pk_bf16_f32 v199, v204, v205
	global_store_dwordx4 v[170:171], v[196:199], off
	v_pk_mul_f32 v[202:203], v[106:107], v[160:161] op_sel_hi:[1,0]
	v_pk_mul_f32 v[204:205], v[104:105], v[160:161] op_sel_hi:[1,0]
	s_nop 1
	v_mov_b32_e32 v196, v228
	v_mov_b32_e32 v197, v229
	v_mov_b32_e32 v198, v230
	v_mov_b32_e32 v199, v231
	v_lshlrev_b32_e32 v200, 16, v196
	v_and_b32_e32 v201, 0xffff0000, v196
	v_lshlrev_b32_e32 v196, 16, v197
	v_and_b32_e32 v197, 0xffff0000, v197
	v_pk_fma_f32 v[202:203], v[142:143], v[202:203], v[196:197]
	v_pk_fma_f32 v[196:197], v[144:145], v[204:205], v[200:201]
	v_lshlrev_b32_e32 v200, 16, v198
	v_and_b32_e32 v201, 0xffff0000, v198
	v_lshlrev_b32_e32 v198, 16, v199
	v_and_b32_e32 v199, 0xffff0000, v199
	v_pk_mul_f32 v[204:205], v[98:99], v[160:161] op_sel_hi:[1,0]
	v_pk_mul_f32 v[160:161], v[96:97], v[160:161] op_sel_hi:[1,0]
	v_pk_fma_f32 v[204:205], v[140:141], v[204:205], v[198:199]
	v_pk_fma_f32 v[160:161], v[138:139], v[160:161], v[200:201]
	v_cvt_pk_bf16_f32 v196, v196, v197
	v_cvt_pk_bf16_f32 v197, v202, v203
	v_cvt_pk_bf16_f32 v198, v160, v161
	v_cvt_pk_bf16_f32 v199, v204, v205
	global_store_dwordx4 v[170:171], v[196:199], off offset:256
	v_lshlrev_b32_e32 v217, 11, v180
	v_lshl_add_u32 v217, v191, 1, v217
	global_load_dwordx4 v[120:123], v217, s[34:35] offset:256 nt
	v_lshlrev_b32_e32 v217, 11, v182
	v_lshl_add_u32 v217, v191, 1, v217
	global_load_dwordx4 v[124:127], v217, s[34:35] nt
	global_load_dwordx4 v[96:99], v217, s[34:35] offset:256 nt
	v_lshlrev_b32_e32 v217, 11, v184
	v_lshl_add_u32 v217, v191, 1, v217
	global_load_dwordx4 v[104:107], v217, s[34:35] nt
	v_add_u32_e32 v170, s15, v176
	v_ashrrev_i32_e32 v171, 31, v170
	v_lshlrev_b64 v[170:171], 11, v[170:171]
	v_lshl_add_u64 v[170:171], s[78:79], 0, v[170:171]
	v_lshl_add_u64 v[170:171], v[170:171], 0, v[154:155]
	ds_read_b32 v160, v177
	s_waitcnt lgkmcnt(0)
; __device__ __forceinline__ unsigned cvt_pk_bf16(float lo, float hi) { const f32x2 v = (f32x2){lo, hi}; return __builtin_bit_cast(unsigned, __builtin_convertvector(v, bf16v2)); }
; __device__ __forceinline__ f32x4 bfx4_lo(u32x4 w) { return (f32x4){bf_lo(w.x), bf_hi(w.x), bf_lo(w.y), bf_hi(w.y)}; }
; __device__ __forceinline__ f32x4 bfx4_hi(u32x4 w) { return (f32x4){bf_lo(w.z), bf_hi(w.z), bf_lo(w.w), bf_hi(w.w)}; }
; __device__ __forceinline__ void fused_epi(f32x4 (&acc)[2][2][4][2], const Unit& u, int wr, int wc, int fr, int fq, LAS unsigned char* xl, int wid, int lane, const FuseArgs& f) {
;     ...
;             for (int m = 0; m < 4; ++m) { const int r = ai * HALF + wr * 64 + m * 16 + fr; const float rstd = S[r];
; #pragma unroll
;                 for (int bj = 0; bj < 2; ++bj) { const size_t off = (size_t)(pm * BM + r) * DM + colb + bj * HALF;
;                     const u32x4 xw = *(const u32x4*)((const bf16_t*)(f.ws + WS_XR) + off);
;                     const f32x4 x0 = bfx4_lo(xw) + Gv[bj][0] * (acc[ai][bj][m][0] * rstd), x1 = bfx4_hi(xw) + Gv[bj][1] * (acc[ai][bj][m][1] * rstd);
;                     if (f.out_f32) { *(f32x4*)(f.xoutf + off) = x0; *(f32x4*)(f.xoutf + off + 4) = x1; acc[ai][bj][m][0] = x0; acc[ai][bj][m][1] = x1; }
;                     else { u32x4 w; w.x = cvt_pk_bf16(x0[0], x0[1]); w.y = cvt_pk_bf16(x0[2], x0[3]); w.z = cvt_pk_bf16(x1[0], x1[1]); w.w = cvt_pk_bf16(x1[2], x1[3]);
;                         *(u32x4*)((bf16_t*)(f.ws + WS_XR) + off) = w; acc[ai][bj][m][0] = bfx4_lo(w); acc[ai][bj][m][1] = bfx4_hi(w); } }
	v_pk_mul_f32 v[202:203], v[118:119], v[160:161] op_sel_hi:[1,0]
	v_pk_mul_f32 v[204:205], v[116:117], v[160:161] op_sel_hi:[1,0]
	v_pk_mul_f32 v[206:207], v[112:113], v[160:161] op_sel_hi:[1,0]
	s_nop 1
	v_mov_b32_e32 v196, v232
	v_mov_b32_e32 v197, v233
	v_mov_b32_e32 v198, v234
	v_mov_b32_e32 v199, v235
	v_lshlrev_b32_e32 v200, 16, v196
	v_and_b32_e32 v201, 0xffff0000, v196
	v_lshlrev_b32_e32 v196, 16, v197
	v_and_b32_e32 v197, 0xffff0000, v197
	v_pk_fma_f32 v[202:203], v[150:151], v[202:203], v[196:197]
	v_pk_fma_f32 v[196:197], v[152:153], v[204:205], v[200:201]
	v_lshlrev_b32_e32 v200, 16, v198
	v_and_b32_e32 v201, 0xffff0000, v198
	v_lshlrev_b32_e32 v198, 16, v199
	v_and_b32_e32 v199, 0xffff0000, v199
	v_pk_mul_f32 v[204:205], v[114:115], v[160:161] op_sel_hi:[1,0]
	v_cvt_pk_bf16_f32 v196, v196, v197
	v_pk_fma_f32 v[204:205], v[146:147], v[204:205], v[198:199]
	v_pk_fma_f32 v[198:199], v[148:149], v[206:207], v[200:201]
	v_cvt_pk_bf16_f32 v197, v202, v203
	v_cvt_pk_bf16_f32 v198, v198, v199
	v_cvt_pk_bf16_f32 v199, v204, v205
	global_store_dwordx4 v[170:171], v[196:199], off
	v_pk_mul_f32 v[202:203], v[90:91], v[160:161] op_sel_hi:[1,0]
	v_pk_mul_f32 v[204:205], v[88:89], v[160:161] op_sel_hi:[1,0]
	s_nop 1
	v_mov_b32_e32 v196, v236
	v_mov_b32_e32 v197, v237
	v_mov_b32_e32 v198, v238
	v_mov_b32_e32 v199, v239
	v_lshlrev_b32_e32 v200, 16, v196
	v_and_b32_e32 v201, 0xffff0000, v196
	v_lshlrev_b32_e32 v196, 16, v197
	v_and_b32_e32 v197, 0xffff0000, v197
	v_pk_fma_f32 v[202:203], v[142:143], v[202:203], v[196:197]
	v_pk_fma_f32 v[196:197], v[144:145], v[204:205], v[200:201]
	v_lshlrev_b32_e32 v200, 16, v198
	v_and_b32_e32 v201, 0xffff0000, v198
	v_lshlrev_b32_e32 v198, 16, v199
	v_and_b32_e32 v199, 0xffff0000, v199
	v_pk_mul_f32 v[204:205], v[82:83], v[160:161] op_sel_hi:[1,0]
	v_pk_mul_f32 v[160:161], v[80:81], v[160:161] op_sel_hi:[1,0]
	v_pk_fma_f32 v[204:205], v[140:141], v[204:205], v[198:199]
	v_pk_fma_f32 v[160:161], v[138:139], v[160:161], v[200:201]
	v_cvt_pk_bf16_f32 v196, v196, v197
	v_cvt_pk_bf16_f32 v197, v202, v203
	v_cvt_pk_bf16_f32 v198, v160, v161
	v_cvt_pk_bf16_f32 v199, v204, v205
	global_store_dwordx4 v[170:171], v[196:199], off offset:256
	v_lshlrev_b32_e32 v217, 11, v184
	v_lshl_add_u32 v217, v191, 1, v217
	global_load_dwordx4 v[112:115], v217, s[34:35] offset:256 nt
	v_lshlrev_b32_e32 v217, 11, v186
	v_lshl_add_u32 v217, v191, 1, v217
	global_load_dwordx4 v[116:119], v217, s[34:35] nt
	global_load_dwordx4 v[88:91], v217, s[34:35] offset:256 nt
	v_lshlrev_b32_e32 v217, 11, v188
	v_lshl_add_u32 v217, v191, 1, v217
	global_load_dwordx4 v[80:83], v217, s[34:35] nt
	v_add_u32_e32 v170, s15, v178
	v_ashrrev_i32_e32 v171, 31, v170
	v_lshlrev_b64 v[170:171], 11, v[170:171]
	v_lshl_add_u64 v[170:171], s[78:79], 0, v[170:171]
	v_lshl_add_u64 v[170:171], v[170:171], 0, v[154:155]
	ds_read_b32 v160, v179
	s_waitcnt lgkmcnt(0)
	v_pk_mul_f32 v[202:203], v[110:111], v[160:161] op_sel_hi:[1,0]
	v_pk_mul_f32 v[204:205], v[108:109], v[160:161] op_sel_hi:[1,0]
	v_pk_mul_f32 v[206:207], v[100:101], v[160:161] op_sel_hi:[1,0]
	s_nop 1
	v_mov_b32_e32 v196, v240
	v_mov_b32_e32 v197, v241
	v_mov_b32_e32 v198, v242
	v_mov_b32_e32 v199, v243
	v_lshlrev_b32_e32 v200, 16, v196
	v_and_b32_e32 v201, 0xffff0000, v196
	v_lshlrev_b32_e32 v196, 16, v197
	v_and_b32_e32 v197, 0xffff0000, v197
	v_pk_fma_f32 v[202:203], v[150:151], v[202:203], v[196:197]
	v_pk_fma_f32 v[196:197], v[152:153], v[204:205], v[200:201]
	v_lshlrev_b32_e32 v200, 16, v198
	v_and_b32_e32 v201, 0xffff0000, v198
	v_lshlrev_b32_e32 v198, 16, v199
	v_and_b32_e32 v199, 0xffff0000, v199
	v_pk_mul_f32 v[204:205], v[102:103], v[160:161] op_sel_hi:[1,0]
	v_cvt_pk_bf16_f32 v196, v196, v197
	v_pk_fma_f32 v[204:205], v[146:147], v[204:205], v[198:199]
	v_pk_fma_f32 v[198:199], v[148:149], v[206:207], v[200:201]
	v_cvt_pk_bf16_f32 v197, v202, v203
	v_cvt_pk_bf16_f32 v198, v198, v199
	v_cvt_pk_bf16_f32 v199, v204, v205
	global_store_dwordx4 v[170:171], v[196:199], off
	v_pk_mul_f32 v[202:203], v[78:79], v[160:161] op_sel_hi:[1,0]
	v_pk_mul_f32 v[204:205], v[76:77], v[160:161] op_sel_hi:[1,0]
	s_nop 1
	v_mov_b32_e32 v196, v244
	v_mov_b32_e32 v197, v245
	v_mov_b32_e32 v198, v246
	v_mov_b32_e32 v199, v247
	v_lshlrev_b32_e32 v200, 16, v196
	v_and_b32_e32 v201, 0xffff0000, v196
	v_lshlrev_b32_e32 v196, 16, v197
	v_and_b32_e32 v197, 0xffff0000, v197
	v_pk_fma_f32 v[202:203], v[142:143], v[202:203], v[196:197]
	v_pk_fma_f32 v[196:197], v[144:145], v[204:205], v[200:201]
	v_lshlrev_b32_e32 v200, 16, v198
	v_and_b32_e32 v201, 0xffff0000, v198
	v_lshlrev_b32_e32 v198, 16, v199
	v_and_b32_e32 v199, 0xffff0000, v199
	v_pk_mul_f32 v[204:205], v[74:75], v[160:161] op_sel_hi:[1,0]
	v_pk_mul_f32 v[160:161], v[72:73], v[160:161] op_sel_hi:[1,0]
	v_pk_fma_f32 v[204:205], v[140:141], v[204:205], v[198:199]
	v_pk_fma_f32 v[160:161], v[138:139], v[160:161], v[200:201]
	v_cvt_pk_bf16_f32 v196, v196, v197
	v_cvt_pk_bf16_f32 v197, v202, v203
	v_cvt_pk_bf16_f32 v198, v160, v161
	v_cvt_pk_bf16_f32 v199, v204, v205
	global_store_dwordx4 v[170:171], v[196:199], off offset:256
	v_lshlrev_b32_e32 v217, 11, v188
	v_lshl_add_u32 v217, v191, 1, v217
	global_load_dwordx4 v[108:111], v217, s[34:35] offset:256 nt
	v_add_u32_e32 v170, s15, v180
	v_ashrrev_i32_e32 v171, 31, v170
	v_lshlrev_b64 v[170:171], 11, v[170:171]
	v_lshl_add_u64 v[170:171], s[78:79], 0, v[170:171]
	v_lshl_add_u64 v[170:171], v[170:171], 0, v[154:155]
	ds_read_b32 v160, v181
	s_waitcnt lgkmcnt(0)
; __device__ __forceinline__ unsigned cvt_pk_bf16(float lo, float hi) { const f32x2 v = (f32x2){lo, hi}; return __builtin_bit_cast(unsigned, __builtin_convertvector(v, bf16v2)); }
; __device__ __forceinline__ f32x4 bfx4_lo(u32x4 w) { return (f32x4){bf_lo(w.x), bf_hi(w.x), bf_lo(w.y), bf_hi(w.y)}; }
; __device__ __forceinline__ f32x4 bfx4_hi(u32x4 w) { return (f32x4){bf_lo(w.z), bf_hi(w.z), bf_lo(w.w), bf_hi(w.w)}; }
; __device__ __forceinline__ void fused_epi(f32x4 (&acc)[2][2][4][2], const Unit& u, int wr, int wc, int fr, int fq, LAS unsigned char* xl, int wid, int lane, const FuseArgs& f) {
;     ...
;             for (int m = 0; m < 4; ++m) { const int r = ai * HALF + wr * 64 + m * 16 + fr; const float rstd = S[r];
; #pragma unroll
;                 for (int bj = 0; bj < 2; ++bj) { const size_t off = (size_t)(pm * BM + r) * DM + colb + bj * HALF;
;                     const u32x4 xw = *(const u32x4*)((const bf16_t*)(f.ws + WS_XR) + off);
;                     const f32x4 x0 = bfx4_lo(xw) + Gv[bj][0] * (acc[ai][bj][m][0] * rstd), x1 = bfx4_hi(xw) + Gv[bj][1] * (acc[ai][bj][m][1] * rstd);
;                     if (f.out_f32) { *(f32x4*)(f.xoutf + off) = x0; *(f32x4*)(f.xoutf + off + 4) = x1; acc[ai][bj][m][0] = x0; acc[ai][bj][m][1] = x1; }
;                     else { u32x4 w; w.x = cvt_pk_bf16(x0[0], x0[1]); w.y = cvt_pk_bf16(x0[2], x0[3]); w.z = cvt_pk_bf16(x1[0], x1[1]); w.w = cvt_pk_bf16(x1[2], x1[3]);
;                         *(u32x4*)((bf16_t*)(f.ws + WS_XR) + off) = w; acc[ai][bj][m][0] = bfx4_lo(w); acc[ai][bj][m][1] = bfx4_hi(w); } }
	v_pk_mul_f32 v[202:203], v[94:95], v[160:161] op_sel_hi:[1,0]
	v_pk_mul_f32 v[204:205], v[92:93], v[160:161] op_sel_hi:[1,0]
	v_pk_mul_f32 v[206:207], v[84:85], v[160:161] op_sel_hi:[1,0]
	s_nop 1
	v_mov_b32_e32 v196, v248
	v_mov_b32_e32 v197, v249
	v_mov_b32_e32 v198, v250
	v_mov_b32_e32 v199, v251
	v_lshlrev_b32_e32 v200, 16, v196
	v_and_b32_e32 v201, 0xffff0000, v196
	v_lshlrev_b32_e32 v196, 16, v197
	v_and_b32_e32 v197, 0xffff0000, v197
	v_pk_fma_f32 v[202:203], v[150:151], v[202:203], v[196:197]
	v_pk_fma_f32 v[196:197], v[152:153], v[204:205], v[200:201]
	v_lshlrev_b32_e32 v200, 16, v198
	v_and_b32_e32 v201, 0xffff0000, v198
	v_lshlrev_b32_e32 v198, 16, v199
	v_and_b32_e32 v199, 0xffff0000, v199
	v_pk_mul_f32 v[204:205], v[86:87], v[160:161] op_sel_hi:[1,0]
	v_cvt_pk_bf16_f32 v196, v196, v197
	v_pk_fma_f32 v[204:205], v[146:147], v[204:205], v[198:199]
	v_pk_fma_f32 v[198:199], v[148:149], v[206:207], v[200:201]
	v_cvt_pk_bf16_f32 v197, v202, v203
	v_cvt_pk_bf16_f32 v198, v198, v199
	v_cvt_pk_bf16_f32 v199, v204, v205
	global_store_dwordx4 v[170:171], v[196:199], off
	v_pk_mul_f32 v[202:203], v[70:71], v[160:161] op_sel_hi:[1,0]
	v_pk_mul_f32 v[204:205], v[68:69], v[160:161] op_sel_hi:[1,0]
	s_waitcnt vmcnt(13)
	s_nop 1
	v_mov_b32_e32 v196, v120
	v_mov_b32_e32 v197, v121
	v_mov_b32_e32 v198, v122
	v_mov_b32_e32 v199, v123
	v_lshlrev_b32_e32 v200, 16, v196
	v_and_b32_e32 v201, 0xffff0000, v196
	v_lshlrev_b32_e32 v196, 16, v197
	v_and_b32_e32 v197, 0xffff0000, v197
	v_pk_fma_f32 v[202:203], v[142:143], v[202:203], v[196:197]
	v_pk_fma_f32 v[196:197], v[144:145], v[204:205], v[200:201]
	v_lshlrev_b32_e32 v200, 16, v198
	v_and_b32_e32 v201, 0xffff0000, v198
	v_lshlrev_b32_e32 v198, 16, v199
	v_and_b32_e32 v199, 0xffff0000, v199
	v_pk_mul_f32 v[204:205], v[66:67], v[160:161] op_sel_hi:[1,0]
	v_pk_mul_f32 v[160:161], v[64:65], v[160:161] op_sel_hi:[1,0]
	v_pk_fma_f32 v[204:205], v[140:141], v[204:205], v[198:199]
	v_pk_fma_f32 v[160:161], v[138:139], v[160:161], v[200:201]
	v_cvt_pk_bf16_f32 v196, v196, v197
	v_cvt_pk_bf16_f32 v197, v202, v203
	v_cvt_pk_bf16_f32 v198, v160, v161
	v_cvt_pk_bf16_f32 v199, v204, v205
	global_store_dwordx4 v[170:171], v[196:199], off offset:256
	v_add_u32_e32 v170, s15, v182
	v_ashrrev_i32_e32 v171, 31, v170
	v_lshlrev_b64 v[170:171], 11, v[170:171]
	v_lshl_add_u64 v[170:171], s[78:79], 0, v[170:171]
	v_lshl_add_u64 v[170:171], v[170:171], 0, v[154:155]
	ds_read_b32 v160, v183
	s_waitcnt lgkmcnt(0)
	v_pk_mul_f32 v[202:203], v[62:63], v[160:161] op_sel_hi:[1,0]
	v_pk_mul_f32 v[204:205], v[60:61], v[160:161] op_sel_hi:[1,0]
	v_pk_mul_f32 v[206:207], v[56:57], v[160:161] op_sel_hi:[1,0]
	s_waitcnt vmcnt(13)
	s_nop 1
	v_mov_b32_e32 v196, v124
	v_mov_b32_e32 v197, v125
	v_mov_b32_e32 v198, v126
	v_mov_b32_e32 v199, v127
	v_lshlrev_b32_e32 v200, 16, v196
	v_and_b32_e32 v201, 0xffff0000, v196
	v_lshlrev_b32_e32 v196, 16, v197
	v_and_b32_e32 v197, 0xffff0000, v197
	v_pk_fma_f32 v[202:203], v[150:151], v[202:203], v[196:197]
	v_pk_fma_f32 v[196:197], v[152:153], v[204:205], v[200:201]
	v_lshlrev_b32_e32 v200, 16, v198
	v_and_b32_e32 v201, 0xffff0000, v198
	v_lshlrev_b32_e32 v198, 16, v199
	v_and_b32_e32 v199, 0xffff0000, v199
	v_pk_mul_f32 v[204:205], v[58:59], v[160:161] op_sel_hi:[1,0]
	v_cvt_pk_bf16_f32 v196, v196, v197
	v_pk_fma_f32 v[204:205], v[146:147], v[204:205], v[198:199]
	v_pk_fma_f32 v[198:199], v[148:149], v[206:207], v[200:201]
	v_cvt_pk_bf16_f32 v197, v202, v203
	v_cvt_pk_bf16_f32 v198, v198, v199
	v_cvt_pk_bf16_f32 v199, v204, v205
	global_store_dwordx4 v[170:171], v[196:199], off
	v_pk_mul_f32 v[202:203], v[46:47], v[160:161] op_sel_hi:[1,0]
	v_pk_mul_f32 v[204:205], v[44:45], v[160:161] op_sel_hi:[1,0]
	s_waitcnt vmcnt(13)
	s_nop 1
	v_mov_b32_e32 v196, v96
	v_mov_b32_e32 v197, v97
	v_mov_b32_e32 v198, v98
	v_mov_b32_e32 v199, v99
	v_lshlrev_b32_e32 v200, 16, v196
	v_and_b32_e32 v201, 0xffff0000, v196
	v_lshlrev_b32_e32 v196, 16, v197
	v_and_b32_e32 v197, 0xffff0000, v197
	v_pk_fma_f32 v[202:203], v[142:143], v[202:203], v[196:197]
	v_pk_fma_f32 v[196:197], v[144:145], v[204:205], v[200:201]
	v_lshlrev_b32_e32 v200, 16, v198
	v_and_b32_e32 v201, 0xffff0000, v198
	v_lshlrev_b32_e32 v198, 16, v199
	v_and_b32_e32 v199, 0xffff0000, v199
	v_pk_mul_f32 v[204:205], v[38:39], v[160:161] op_sel_hi:[1,0]
	v_pk_mul_f32 v[160:161], v[36:37], v[160:161] op_sel_hi:[1,0]
	v_pk_fma_f32 v[204:205], v[140:141], v[204:205], v[198:199]
	v_pk_fma_f32 v[160:161], v[138:139], v[160:161], v[200:201]
	v_cvt_pk_bf16_f32 v196, v196, v197
	v_cvt_pk_bf16_f32 v197, v202, v203
	v_cvt_pk_bf16_f32 v198, v160, v161
	v_cvt_pk_bf16_f32 v199, v204, v205
	global_store_dwordx4 v[170:171], v[196:199], off offset:256
	v_add_u32_e32 v170, s15, v184
	v_ashrrev_i32_e32 v171, 31, v170
	v_lshlrev_b64 v[170:171], 11, v[170:171]
	v_lshl_add_u64 v[170:171], s[78:79], 0, v[170:171]
	v_lshl_add_u64 v[170:171], v[170:171], 0, v[154:155]
	ds_read_b32 v160, v185
	s_waitcnt lgkmcnt(0)
	v_pk_mul_f32 v[202:203], v[54:55], v[160:161] op_sel_hi:[1,0]
	v_pk_mul_f32 v[204:205], v[52:53], v[160:161] op_sel_hi:[1,0]
	v_pk_mul_f32 v[206:207], v[48:49], v[160:161] op_sel_hi:[1,0]
	s_waitcnt vmcnt(13)
; __device__ __forceinline__ unsigned cvt_pk_bf16(float lo, float hi) { const f32x2 v = (f32x2){lo, hi}; return __builtin_bit_cast(unsigned, __builtin_convertvector(v, bf16v2)); }
; __device__ __forceinline__ f32x4 bfx4_lo(u32x4 w) { return (f32x4){bf_lo(w.x), bf_hi(w.x), bf_lo(w.y), bf_hi(w.y)}; }
; __device__ __forceinline__ f32x4 bfx4_hi(u32x4 w) { return (f32x4){bf_lo(w.z), bf_hi(w.z), bf_lo(w.w), bf_hi(w.w)}; }
; __device__ __forceinline__ void fused_epi(f32x4 (&acc)[2][2][4][2], const Unit& u, int wr, int wc, int fr, int fq, LAS unsigned char* xl, int wid, int lane, const FuseArgs& f) {
;     ...
;             for (int m = 0; m < 4; ++m) { const int r = ai * HALF + wr * 64 + m * 16 + fr; const float rstd = S[r];
; #pragma unroll
;                 for (int bj = 0; bj < 2; ++bj) { const size_t off = (size_t)(pm * BM + r) * DM + colb + bj * HALF;
;                     const u32x4 xw = *(const u32x4*)((const bf16_t*)(f.ws + WS_XR) + off);
;                     const f32x4 x0 = bfx4_lo(xw) + Gv[bj][0] * (acc[ai][bj][m][0] * rstd), x1 = bfx4_hi(xw) + Gv[bj][1] * (acc[ai][bj][m][1] * rstd);
;                     if (f.out_f32) { *(f32x4*)(f.xoutf + off) = x0; *(f32x4*)(f.xoutf + off + 4) = x1; acc[ai][bj][m][0] = x0; acc[ai][bj][m][1] = x1; }
;                     else { u32x4 w; w.x = cvt_pk_bf16(x0[0], x0[1]); w.y = cvt_pk_bf16(x0[2], x0[3]); w.z = cvt_pk_bf16(x1[0], x1[1]); w.w = cvt_pk_bf16(x1[2], x1[3]);
;                         *(u32x4*)((bf16_t*)(f.ws + WS_XR) + off) = w; acc[ai][bj][m][0] = bfx4_lo(w); acc[ai][bj][m][1] = bfx4_hi(w); } }
	s_nop 1
	v_mov_b32_e32 v196, v104
	v_mov_b32_e32 v197, v105
	v_mov_b32_e32 v198, v106
	v_mov_b32_e32 v199, v107
	v_lshlrev_b32_e32 v200, 16, v196
	v_and_b32_e32 v201, 0xffff0000, v196
	v_lshlrev_b32_e32 v196, 16, v197
	v_and_b32_e32 v197, 0xffff0000, v197
	v_pk_fma_f32 v[202:203], v[150:151], v[202:203], v[196:197]
	v_pk_fma_f32 v[196:197], v[152:153], v[204:205], v[200:201]
	v_lshlrev_b32_e32 v200, 16, v198
	v_and_b32_e32 v201, 0xffff0000, v198
	v_lshlrev_b32_e32 v198, 16, v199
	v_and_b32_e32 v199, 0xffff0000, v199
	v_pk_mul_f32 v[204:205], v[50:51], v[160:161] op_sel_hi:[1,0]
	v_cvt_pk_bf16_f32 v196, v196, v197
	v_pk_fma_f32 v[204:205], v[146:147], v[204:205], v[198:199]
	v_pk_fma_f32 v[198:199], v[148:149], v[206:207], v[200:201]
	v_cvt_pk_bf16_f32 v197, v202, v203
	v_cvt_pk_bf16_f32 v198, v198, v199
	v_cvt_pk_bf16_f32 v199, v204, v205
	global_store_dwordx4 v[170:171], v[196:199], off
	v_pk_mul_f32 v[202:203], v[30:31], v[160:161] op_sel_hi:[1,0]
	v_pk_mul_f32 v[204:205], v[28:29], v[160:161] op_sel_hi:[1,0]
	s_waitcnt vmcnt(11)
	s_nop 1
	v_mov_b32_e32 v196, v112
	v_mov_b32_e32 v197, v113
	v_mov_b32_e32 v198, v114
	v_mov_b32_e32 v199, v115
	v_lshlrev_b32_e32 v200, 16, v196
	v_and_b32_e32 v201, 0xffff0000, v196
	v_lshlrev_b32_e32 v196, 16, v197
	v_and_b32_e32 v197, 0xffff0000, v197
	v_pk_fma_f32 v[202:203], v[142:143], v[202:203], v[196:197]
	v_pk_fma_f32 v[196:197], v[144:145], v[204:205], v[200:201]
	v_lshlrev_b32_e32 v200, 16, v198
	v_and_b32_e32 v201, 0xffff0000, v198
	v_lshlrev_b32_e32 v198, 16, v199
	v_and_b32_e32 v199, 0xffff0000, v199
	v_pk_mul_f32 v[204:205], v[22:23], v[160:161] op_sel_hi:[1,0]
	v_pk_mul_f32 v[160:161], v[20:21], v[160:161] op_sel_hi:[1,0]
	v_pk_fma_f32 v[204:205], v[140:141], v[204:205], v[198:199]
	v_pk_fma_f32 v[160:161], v[138:139], v[160:161], v[200:201]
	v_cvt_pk_bf16_f32 v196, v196, v197
	v_cvt_pk_bf16_f32 v197, v202, v203
	v_cvt_pk_bf16_f32 v198, v160, v161
	v_cvt_pk_bf16_f32 v199, v204, v205
	global_store_dwordx4 v[170:171], v[196:199], off offset:256
	v_add_u32_e32 v170, s15, v186
	v_ashrrev_i32_e32 v171, 31, v170
	v_lshlrev_b64 v[170:171], 11, v[170:171]
	v_lshl_add_u64 v[170:171], s[78:79], 0, v[170:171]
	v_lshl_add_u64 v[170:171], v[170:171], 0, v[154:155]
	ds_read_b32 v160, v187
	s_waitcnt lgkmcnt(0)
	v_pk_mul_f32 v[202:203], v[42:43], v[160:161] op_sel_hi:[1,0]
	v_pk_mul_f32 v[204:205], v[40:41], v[160:161] op_sel_hi:[1,0]
	v_pk_mul_f32 v[206:207], v[32:33], v[160:161] op_sel_hi:[1,0]
	s_waitcnt vmcnt(11)
	s_nop 1
	v_mov_b32_e32 v196, v116
	v_mov_b32_e32 v197, v117
	v_mov_b32_e32 v198, v118
	v_mov_b32_e32 v199, v119
	v_lshlrev_b32_e32 v200, 16, v196
	v_and_b32_e32 v201, 0xffff0000, v196
	v_lshlrev_b32_e32 v196, 16, v197
	v_and_b32_e32 v197, 0xffff0000, v197
	v_pk_fma_f32 v[202:203], v[150:151], v[202:203], v[196:197]
	v_pk_fma_f32 v[196:197], v[152:153], v[204:205], v[200:201]
	v_lshlrev_b32_e32 v200, 16, v198
	v_and_b32_e32 v201, 0xffff0000, v198
	v_lshlrev_b32_e32 v198, 16, v199
	v_and_b32_e32 v199, 0xffff0000, v199
	v_pk_mul_f32 v[204:205], v[34:35], v[160:161] op_sel_hi:[1,0]
	v_cvt_pk_bf16_f32 v196, v196, v197
	v_pk_fma_f32 v[204:205], v[146:147], v[204:205], v[198:199]
	v_pk_fma_f32 v[198:199], v[148:149], v[206:207], v[200:201]
	v_cvt_pk_bf16_f32 v197, v202, v203
	v_cvt_pk_bf16_f32 v198, v198, v199
	v_cvt_pk_bf16_f32 v199, v204, v205
	global_store_dwordx4 v[170:171], v[196:199], off
	v_pk_mul_f32 v[202:203], v[14:15], v[160:161] op_sel_hi:[1,0]
	v_pk_mul_f32 v[204:205], v[12:13], v[160:161] op_sel_hi:[1,0]
	s_waitcnt vmcnt(11)
	s_nop 1
	v_mov_b32_e32 v196, v88
	v_mov_b32_e32 v197, v89
	v_mov_b32_e32 v198, v90
	v_mov_b32_e32 v199, v91
	v_lshlrev_b32_e32 v200, 16, v196
	v_and_b32_e32 v201, 0xffff0000, v196
	v_lshlrev_b32_e32 v196, 16, v197
	v_and_b32_e32 v197, 0xffff0000, v197
	v_pk_fma_f32 v[202:203], v[142:143], v[202:203], v[196:197]
	v_pk_fma_f32 v[196:197], v[144:145], v[204:205], v[200:201]
	v_lshlrev_b32_e32 v200, 16, v198
	v_and_b32_e32 v201, 0xffff0000, v198
	v_lshlrev_b32_e32 v198, 16, v199
	v_and_b32_e32 v199, 0xffff0000, v199
	v_pk_mul_f32 v[204:205], v[10:11], v[160:161] op_sel_hi:[1,0]
	v_pk_mul_f32 v[160:161], v[8:9], v[160:161] op_sel_hi:[1,0]
	v_pk_fma_f32 v[204:205], v[140:141], v[204:205], v[198:199]
	v_pk_fma_f32 v[160:161], v[138:139], v[160:161], v[200:201]
	v_cvt_pk_bf16_f32 v196, v196, v197
	v_cvt_pk_bf16_f32 v197, v202, v203
	v_cvt_pk_bf16_f32 v198, v160, v161
	v_cvt_pk_bf16_f32 v199, v204, v205
	global_store_dwordx4 v[170:171], v[196:199], off offset:256
	v_add_u32_e32 v170, s15, v188
	v_ashrrev_i32_e32 v171, 31, v170
	v_lshlrev_b64 v[170:171], 11, v[170:171]
	v_lshl_add_u64 v[170:171], s[78:79], 0, v[170:171]
	v_lshl_add_u64 v[154:155], v[170:171], 0, v[154:155]
	ds_read_b32 v160, v189
	s_waitcnt lgkmcnt(0)
	v_pk_mul_f32 v[200:201], v[26:27], v[160:161] op_sel_hi:[1,0]
	v_pk_mul_f32 v[202:203], v[24:25], v[160:161] op_sel_hi:[1,0]
	s_waitcnt vmcnt(11)
	s_nop 1
	v_mov_b32_e32 v196, v80
	v_mov_b32_e32 v197, v81
	v_mov_b32_e32 v198, v82
	v_mov_b32_e32 v199, v83
	v_lshlrev_b32_e32 v170, 16, v196
	v_and_b32_e32 v171, 0xffff0000, v196
	v_lshlrev_b32_e32 v196, 16, v197
	v_and_b32_e32 v197, 0xffff0000, v197
	v_pk_fma_f32 v[150:151], v[150:151], v[200:201], v[196:197]
	v_pk_fma_f32 v[152:153], v[152:153], v[202:203], v[170:171]
	v_lshlrev_b32_e32 v170, 16, v198
	v_and_b32_e32 v171, 0xffff0000, v198
	v_lshlrev_b32_e32 v196, 16, v199
	v_and_b32_e32 v197, 0xffff0000, v199
	v_pk_mul_f32 v[198:199], v[18:19], v[160:161] op_sel_hi:[1,0]
	v_pk_mul_f32 v[200:201], v[16:17], v[160:161] op_sel_hi:[1,0]
	v_pk_fma_f32 v[196:197], v[146:147], v[198:199], v[196:197]
	v_pk_fma_f32 v[148:149], v[148:149], v[200:201], v[170:171]
	v_cvt_pk_bf16_f32 v146, v152, v153
	v_cvt_pk_bf16_f32 v147, v150, v151
	v_cvt_pk_bf16_f32 v148, v148, v149
	v_cvt_pk_bf16_f32 v149, v196, v197
	global_store_dwordx4 v[154:155], v[146:149], off
	v_pk_mul_f32 v[152:153], v[6:7], v[160:161] op_sel_hi:[1,0]
	v_pk_mul_f32 v[170:171], v[4:5], v[160:161] op_sel_hi:[1,0]
	s_waitcnt vmcnt(9)
	s_nop 1
	v_mov_b32_e32 v146, v108
	v_mov_b32_e32 v147, v109
	v_mov_b32_e32 v148, v110
	v_mov_b32_e32 v149, v111
	v_lshlrev_b32_e32 v150, 16, v146
	v_and_b32_e32 v151, 0xffff0000, v146
	v_lshlrev_b32_e32 v146, 16, v147
	v_and_b32_e32 v147, 0xffff0000, v147
	v_pk_fma_f32 v[142:143], v[142:143], v[152:153], v[146:147]
	v_pk_fma_f32 v[144:145], v[144:145], v[170:171], v[150:151]
	v_lshlrev_b32_e32 v146, 16, v148
	v_and_b32_e32 v147, 0xffff0000, v148
	v_lshlrev_b32_e32 v148, 16, v149
	v_and_b32_e32 v149, 0xffff0000, v149
	v_pk_mul_f32 v[150:151], v[2:3], v[160:161] op_sel_hi:[1,0]
	v_pk_mul_f32 v[152:153], v[0:1], v[160:161] op_sel_hi:[1,0]
	v_pk_fma_f32 v[148:149], v[140:141], v[150:151], v[148:149]
	v_pk_fma_f32 v[140:141], v[138:139], v[152:153], v[146:147]
	v_cvt_pk_bf16_f32 v138, v144, v145
	v_cvt_pk_bf16_f32 v139, v142, v143
	v_cvt_pk_bf16_f32 v140, v140, v141
	v_cvt_pk_bf16_f32 v141, v148, v149
	global_store_dwordx4 v[154:155], v[138:141], off offset:256
	s_branch .LBB0_248

; __device__ __forceinline__ f32x4 bfx4_lo(u32x4 w) { return (f32x4){bf_lo(w.x), bf_hi(w.x), bf_lo(w.y), bf_hi(w.y)}; }
; __device__ __forceinline__ void phase_rows(const Params& p, const RowArgs& a, int G, int wave, int lane) {
;     ...
;         if (bmaj) mp = (it < ppw) ? (gw / wpb) * (SEQ / 2) + (gw % wpb) + it * wpb : ML / 2 + gw + (it - ppw) * NGW;
;         else mp = ((a.ctx_only && !bmaj) ? ML / 2 : 0) + gw + it * NGW;
;         if (mp >= a.nrows / 2) break;
;         const int m0 = 2 * mp; const bool isl = m0 < ML; const int rb = isl ? (m0 >> 12) : 8;
;         const bool use_y = a.has_y && !(a.lat_no_y && isl);
;         const size_t xoff = isl ? (size_t)m0 * DM : (size_t)(m0 - ML) * DM;
;         const void* xrb = isl ? a.xlat : a.xctx; void* xob = isl ? a.olat : a.octx;
;         bf16_t* xn = XN + (size_t)m0 * DM;
;         const size_t moff = (size_t)rb * NMOD;
;         f32x4 v[2][4], y[2][4];
;         if (a.xin_f32) {
; #pragma unroll
;             for (int u = 0; u < 2; ++u)
; #pragma unroll
;                 for (int j = 0; j < 4; ++j) v[u][j] = *(const f32x4*)((const float*)xrb + xoff + u * DM + 8 * lane + 512 * (j >> 1) + 4 * (j & 1));
;         } else {
; #pragma unroll
;             for (int u = 0; u < 2; ++u)
; #pragma unroll
;                 for (int jb = 0; jb < 2; ++jb) { const u32x4 xw = *(const u32x4*)((const bf16_t*)xrb + xoff + u * DM + 8 * lane + 512 * jb); v[u][2 * jb] = bfx4_lo(xw); v[u][2 * jb + 1] = bfx4_hi(xw); }
;         }
;         if (use_y) {
;             if (isl || !a.ctx_split) {
; #pragma unroll
;                 for (int u = 0; u < 2; ++u)
; #pragma unroll
;                     for (int jb = 0; jb < 2; ++jb) { const u32x4 yw = *(const u32x4*)(xn + u * DM + 8 * lane + 512 * jb); y[u][2 * jb] = bfx4_lo(yw); y[u][2 * jb + 1] = bfx4_hi(yw); }
;             } else {
;                 const float* part = (const float*)p.out;
; #pragma unroll
;                 for (int u = 0; u < 2; ++u)
; #pragma unroll
;                     for (int j = 0; j < 4; ++j) { const float* pp = part + (size_t)(m0 + u - ML) * DM + 8 * lane + 512 * (j >> 1) + 4 * (j & 1); f32x4 s = *(const f32x4*)pp;
; #pragma unroll
;                         for (int k = 1; k < pg8::KSPLIT; ++k) s += *(const f32x4*)(pp + (size_t)k * MC * DM);
;                         y[u][j] = s; }
.LBB0_327:
	s_cmpk_gt_i32 s11, 0x43ff
	s_mov_b64 s[0:1], -1
	s_cbranch_scc1 .LBB0_321
	s_lshl_b32 s4, s11, 1
	s_cmpk_lt_i32 s11, 0x4000
	s_cselect_b64 s[0:1], -1, 0
	s_ashr_i32 s5, s4, 31
	s_add_i32 s30, s4, 0xffff8000
	s_cmpk_gt_i32 s11, 0x3fff
	s_cselect_b64 s[8:9], -1, 0
	s_and_b64 s[6:7], s[8:9], exec
	s_cselect_b32 s7, 0, s5
	s_cselect_b32 s6, s30, s4
	s_cselect_b32 s21, s99, s79
	s_cselect_b32 s24, s98, s78
	s_lshl_b64 s[22:23], s[6:7], 11
	s_add_u32 s22, s24, s22
	s_addc_u32 s23, s21, s23
	global_load_dwordx4 v[116:119], v170, s[22:23] nt
	global_load_dwordx4 v[112:115], v170, s[22:23] offset:1024 nt
	global_load_dwordx4 v[108:111], v170, s[22:23] offset:2048 nt
	global_load_dwordx4 v[104:107], v170, s[22:23] offset:3072 nt
	v_lshl_add_u64 v[248:249], s[22:23], 0, v[250:251]
	s_add_i32 s32, s11, s52
	s_cmpk_lt_i32 s32, 0x4000
	s_cselect_b32 s32, 1, 0
	v_readlane_b32 vcc_lo, v254, 17
	s_nop 0
	s_and_b32 s32, s32, vcc_lo
	s_and_b64 vcc, exec, s[0:1]
	s_cbranch_vccnz .LBB0_330
	s_lshl_b64 s[22:23], s[30:31], 12
	v_lshl_add_u64 v[88:89], v[176:177], 0, s[22:23]
	v_add_co_u32_e32 v96, vcc, 0x800000, v88
	global_load_dwordx4 v[84:87], v[88:89], off offset:16 nt
	global_load_dwordx4 v[80:83], v[88:89], off nt
	s_mov_b64 s[24:25], 0x800000
	v_addc_co_u32_e32 v97, vcc, 0, v89, vcc
	v_lshl_add_u64 v[94:95], v[88:89], 0, s[24:25]
	global_load_dwordx4 v[90:93], v[96:97], off nt
	global_load_dwordx4 v[126:129], v[94:95], off offset:16 nt
	s_mov_b64 s[26:27], 0x1000000
	v_add_co_u32_e32 v120, vcc, 0x1000000, v88
	s_mov_b64 s[28:29], 0x1800000
	s_nop 0
	v_addc_co_u32_e32 v121, vcc, 0, v89, vcc
	v_add_co_u32_e32 v122, vcc, 0x1800000, v88
	v_lshl_add_u64 v[100:101], v[88:89], 0, s[28:29]
	s_nop 0
	v_addc_co_u32_e32 v123, vcc, 0, v89, vcc
	v_add_co_u32_e32 v102, vcc, 0x2000000, v88
	s_mov_b64 s[34:35], 0x2000000
	s_nop 0
	v_addc_co_u32_e32 v103, vcc, 0, v89, vcc
	v_add_co_u32_e32 v124, vcc, 0x2800000, v88
	s_mov_b64 s[62:63], 0x2800000
	s_nop 0
	v_addc_co_u32_e32 v125, vcc, 0, v89, vcc
	s_mov_b64 s[64:65], 0x3000000
	v_lshl_add_u64 v[142:143], v[88:89], 0, s[64:65]
	s_mov_b64 s[68:69], 0x3800000
	v_lshl_add_u64 v[146:147], v[88:89], 0, s[68:69]
	s_mov_b64 s[70:71], 0x800800
	s_mov_b64 s[74:75], 0x1000800
	s_mov_b64 s[76:77], 0x1800800
	s_mov_b64 s[94:95], 0x2000800
	s_mov_b64 s[16:17], 0x2800800
	s_mov_b32 s38, s96
	s_mov_b64 s[96:97], 0x3000800
	s_mov_b64 s[36:37], 0x3800800
	s_add_i32 s30, s4, 0xffff8001
	s_lshl_b64 s[22:23], s[30:31], 12
	s_mov_b32 s21, 0x1000000
	s_waitcnt vmcnt(1)
	v_pk_add_f32 v[98:99], v[82:83], v[92:93]
	v_lshl_add_u64 v[92:93], v[88:89], 0, s[26:27]
	v_pk_add_f32 v[90:91], v[80:81], v[90:91]
	global_load_dwordx4 v[80:83], v[120:121], off nt
	s_nop 0
	global_load_dwordx4 v[92:95], v[92:93], off offset:16 nt
	s_waitcnt vmcnt(2)
	v_pk_add_f32 v[86:87], v[86:87], v[128:129]
	v_pk_add_f32 v[84:85], v[84:85], v[126:127]
	s_waitcnt vmcnt(1)
	v_pk_add_f32 v[98:99], v[98:99], v[82:83]
	v_pk_add_f32 v[90:91], v[90:91], v[80:81]
	global_load_dwordx4 v[80:83], v[122:123], off nt
	global_load_dwordx4 v[130:133], v[100:101], off offset:16 nt
	v_lshl_add_u64 v[100:101], v[88:89], 0, s[34:35]
	s_waitcnt vmcnt(2)
	v_pk_add_f32 v[86:87], v[86:87], v[94:95]
	v_pk_add_f32 v[84:85], v[84:85], v[92:93]
	s_waitcnt vmcnt(1)
	v_pk_add_f32 v[98:99], v[98:99], v[82:83]
	v_pk_add_f32 v[90:91], v[90:91], v[80:81]
	global_load_dwordx4 v[80:83], v[102:103], off nt
	global_load_dwordx4 v[134:137], v[100:101], off offset:16 nt
	v_lshl_add_u64 v[100:101], v[88:89], 0, s[62:63]
	s_waitcnt vmcnt(2)
	v_pk_add_f32 v[86:87], v[86:87], v[132:133]
	v_pk_add_f32 v[84:85], v[84:85], v[130:131]
	s_waitcnt vmcnt(1)
	v_pk_add_f32 v[98:99], v[98:99], v[82:83]
	v_pk_add_f32 v[90:91], v[90:91], v[80:81]
	global_load_dwordx4 v[80:83], v[124:125], off nt
	global_load_dwordx4 v[138:141], v[100:101], off offset:16 nt
	v_add_co_u32_e32 v100, vcc, 0x3000000, v88
	s_waitcnt vmcnt(2)
	v_pk_add_f32 v[86:87], v[86:87], v[136:137]
	v_addc_co_u32_e32 v101, vcc, 0, v89, vcc
	v_pk_add_f32 v[84:85], v[84:85], v[134:135]
	s_waitcnt vmcnt(1)
	v_pk_add_f32 v[98:99], v[98:99], v[82:83]
	v_pk_add_f32 v[90:91], v[90:91], v[80:81]
	global_load_dwordx4 v[80:83], v[100:101], off nt
	s_nop 0
	global_load_dwordx4 v[142:145], v[142:143], off offset:16 nt
	s_waitcnt vmcnt(2)
	v_pk_add_f32 v[84:85], v[84:85], v[138:139]
	v_pk_add_f32 v[86:87], v[86:87], v[140:141]
	s_waitcnt vmcnt(1)
	v_pk_add_f32 v[150:151], v[90:91], v[80:81]
	v_add_co_u32_e32 v90, vcc, 0x3800000, v88
	v_pk_add_f32 v[98:99], v[98:99], v[82:83]
	s_nop 0
	v_addc_co_u32_e32 v91, vcc, 0, v89, vcc
	global_load_dwordx4 v[80:83], v[90:91], off nt
	s_nop 0
	global_load_dwordx4 v[146:149], v[146:147], off offset:16 nt
	s_nop 0
	global_load_dwordx4 v[92:95], v[88:89], off offset:2064 nt
	global_load_dwordx4 v[126:129], v[88:89], off offset:2048 nt
	s_waitcnt vmcnt(4)
	v_pk_add_f32 v[84:85], v[84:85], v[142:143]
	v_pk_add_f32 v[86:87], v[86:87], v[144:145]
	s_waitcnt vmcnt(3)
	v_pk_add_f32 v[82:83], v[98:99], v[82:83]
	v_lshl_add_u64 v[98:99], v[88:89], 0, s[70:71]
	global_load_dwordx4 v[130:133], v[96:97], off offset:2048 nt
	s_nop 0
	global_load_dwordx4 v[96:99], v[98:99], off offset:16 nt
	s_waitcnt vmcnt(4)
	v_pk_add_f32 v[86:87], v[86:87], v[148:149]
	v_pk_add_f32 v[84:85], v[84:85], v[146:147]
	v_pk_add_f32 v[80:81], v[150:151], v[80:81]
	s_waitcnt vmcnt(1)
	v_pk_add_f32 v[136:137], v[126:127], v[130:131]
	v_lshl_add_u64 v[130:131], v[88:89], 0, s[74:75]
	v_pk_add_f32 v[134:135], v[128:129], v[132:133]
	global_load_dwordx4 v[126:129], v[120:121], off offset:2048 nt
	s_nop 0
	global_load_dwordx4 v[130:133], v[130:131], off offset:16 nt
	s_waitcnt vmcnt(2)
; __device__ __forceinline__ void phase_rows(const Params& p, const RowArgs& a, int G, int wave, int lane) {
;     ...
;                     for (int j = 0; j < 4; ++j) { const float* pp = part + (size_t)(m0 + u - ML) * DM + 8 * lane + 512 * (j >> 1) + 4 * (j & 1); f32x4 s = *(const f32x4*)pp;
; #pragma unroll
;                         for (int k = 1; k < pg8::KSPLIT; ++k) s += *(const f32x4*)(pp + (size_t)k * MC * DM);
;                         y[u][j] = s; }
	v_pk_add_f32 v[92:93], v[92:93], v[96:97]
	v_pk_add_f32 v[94:95], v[94:95], v[98:99]
	s_waitcnt vmcnt(1)
	v_pk_add_f32 v[136:137], v[136:137], v[126:127]
	v_lshl_add_u64 v[126:127], v[88:89], 0, s[76:77]
	v_pk_add_f32 v[134:135], v[134:135], v[128:129]
	global_load_dwordx4 v[120:123], v[122:123], off offset:2048 nt
	s_nop 0
	global_load_dwordx4 v[126:129], v[126:127], off offset:16 nt
	s_waitcnt vmcnt(2)
	v_pk_add_f32 v[92:93], v[92:93], v[130:131]
	v_pk_add_f32 v[94:95], v[94:95], v[132:133]
	s_waitcnt vmcnt(1)
	v_pk_add_f32 v[138:139], v[134:135], v[122:123]
	v_lshl_add_u64 v[134:135], v[88:89], 0, s[94:95]
	v_pk_add_f32 v[140:141], v[136:137], v[120:121]
	global_load_dwordx4 v[120:123], v[102:103], off offset:2048 nt
	s_nop 0
	global_load_dwordx4 v[134:137], v[134:135], off offset:16 nt
	s_waitcnt vmcnt(2)
	v_pk_add_f32 v[92:93], v[92:93], v[126:127]
	v_pk_add_f32 v[94:95], v[94:95], v[128:129]
	s_waitcnt vmcnt(1)
	v_pk_add_f32 v[102:103], v[138:139], v[122:123]
	v_lshl_add_u64 v[138:139], v[88:89], 0, s[16:17]
	v_pk_add_f32 v[142:143], v[140:141], v[120:121]
	global_load_dwordx4 v[120:123], v[124:125], off offset:2048 nt
	s_nop 0
	global_load_dwordx4 v[138:141], v[138:139], off offset:16 nt
	s_waitcnt vmcnt(2)
	v_pk_add_f32 v[92:93], v[92:93], v[134:135]
	v_pk_add_f32 v[94:95], v[94:95], v[136:137]
	s_waitcnt vmcnt(1)
	v_pk_add_f32 v[142:143], v[142:143], v[120:121]
	v_lshl_add_u64 v[120:121], v[88:89], 0, s[96:97]
	v_pk_add_f32 v[124:125], v[102:103], v[122:123]
	global_load_dwordx4 v[100:103], v[100:101], off offset:2048 nt
	s_nop 0
	global_load_dwordx4 v[120:123], v[120:121], off offset:16 nt
	s_waitcnt vmcnt(2)
	v_pk_add_f32 v[92:93], v[92:93], v[138:139]
	v_pk_add_f32 v[94:95], v[94:95], v[140:141]
	s_waitcnt vmcnt(1)
	v_pk_add_f32 v[142:143], v[142:143], v[100:101]
	v_lshl_add_u64 v[100:101], v[88:89], 0, s[36:37]
	v_pk_add_f32 v[124:125], v[124:125], v[102:103]
	global_load_dwordx4 v[88:91], v[90:91], off offset:2048 nt
	s_nop 0
	global_load_dwordx4 v[100:103], v[100:101], off offset:16 nt
	s_waitcnt vmcnt(2)
	v_pk_add_f32 v[92:93], v[92:93], v[120:121]
	v_lshl_add_u64 v[120:121], v[176:177], 0, s[22:23]
	v_pk_add_f32 v[94:95], v[94:95], v[122:123]
	v_add_co_u32_e32 v122, vcc, s55, v120
	v_lshl_add_u64 v[128:129], v[120:121], 0, s[24:25]
	s_nop 0
	v_addc_co_u32_e32 v123, vcc, 0, v121, vcc
	v_add_co_u32_e32 v132, vcc, s21, v120
	s_mov_b32 s21, 0x1800000
	s_nop 0
	v_addc_co_u32_e32 v133, vcc, 0, v121, vcc
	v_lshl_add_u64 v[140:141], v[120:121], 0, s[28:29]
	s_waitcnt vmcnt(1)
	v_pk_add_f32 v[90:91], v[124:125], v[90:91]
	s_waitcnt vmcnt(0)
	v_pk_add_f32 v[94:95], v[94:95], v[102:103]
	v_pk_add_f32 v[92:93], v[92:93], v[100:101]
	global_load_dwordx4 v[100:103], v[120:121], off offset:16 nt
	global_load_dwordx4 v[96:99], v[120:121], off nt
	global_load_dwordx4 v[124:127], v[122:123], off nt
	s_nop 0
	global_load_dwordx4 v[128:131], v[128:129], off offset:16 nt
	v_pk_add_f32 v[88:89], v[142:143], v[88:89]
	v_lshl_add_u64 v[142:143], v[120:121], 0, s[34:35]
	s_waitcnt vmcnt(1)
	v_pk_add_f32 v[136:137], v[96:97], v[124:125]
	v_lshl_add_u64 v[124:125], v[120:121], 0, s[26:27]
	v_pk_add_f32 v[134:135], v[98:99], v[126:127]
	global_load_dwordx4 v[96:99], v[132:133], off nt
	s_nop 0
	global_load_dwordx4 v[124:127], v[124:125], off offset:16 nt
	s_waitcnt vmcnt(2)
	v_pk_add_f32 v[102:103], v[102:103], v[130:131]
	v_pk_add_f32 v[100:101], v[100:101], v[128:129]
	v_lshl_add_u64 v[128:129], v[120:121], 0, s[70:71]
	s_waitcnt vmcnt(1)
	v_pk_add_f32 v[138:139], v[136:137], v[96:97]
	v_add_co_u32_e32 v136, vcc, s21, v120
	v_pk_add_f32 v[134:135], v[134:135], v[98:99]
	s_nop 0
	v_addc_co_u32_e32 v137, vcc, 0, v121, vcc
	global_load_dwordx4 v[96:99], v[136:137], off nt
	global_load_dwordx4 v[178:181], v[140:141], off offset:16 nt
	s_brev_b32 s21, 64
	v_add_co_u32_e32 v140, vcc, s21, v120
	s_mov_b32 s21, 0x2800000
	s_nop 0
	v_addc_co_u32_e32 v141, vcc, 0, v121, vcc
	v_add_co_u32_e32 v144, vcc, s21, v120
	s_mov_b32 s21, 0x3000000
	s_nop 0
	v_addc_co_u32_e32 v145, vcc, 0, v121, vcc
	v_add_co_u32_e32 v148, vcc, s21, v120
	s_mov_b32 s21, 0x3800000
	s_nop 0
	v_addc_co_u32_e32 v149, vcc, 0, v121, vcc
	v_add_co_u32_e32 v152, vcc, s21, v120
	s_waitcnt vmcnt(2)
	v_pk_add_f32 v[102:103], v[102:103], v[126:127]
	v_addc_co_u32_e32 v153, vcc, 0, v121, vcc
	v_pk_add_f32 v[100:101], v[100:101], v[124:125]
	s_waitcnt vmcnt(1)
	v_pk_add_f32 v[134:135], v[134:135], v[98:99]
	v_pk_add_f32 v[138:139], v[138:139], v[96:97]
	global_load_dwordx4 v[96:99], v[140:141], off nt
	global_load_dwordx4 v[182:185], v[142:143], off offset:16 nt
	v_lshl_add_u64 v[142:143], v[120:121], 0, s[62:63]
	s_waitcnt vmcnt(2)
; __device__ __forceinline__ void phase_rows(const Params& p, const RowArgs& a, int G, int wave, int lane) {
;     ...
;                     for (int j = 0; j < 4; ++j) { const float* pp = part + (size_t)(m0 + u - ML) * DM + 8 * lane + 512 * (j >> 1) + 4 * (j & 1); f32x4 s = *(const f32x4*)pp;
; #pragma unroll
;                         for (int k = 1; k < pg8::KSPLIT; ++k) s += *(const f32x4*)(pp + (size_t)k * MC * DM);
;                         y[u][j] = s; }
	v_pk_add_f32 v[102:103], v[102:103], v[180:181]
	v_pk_add_f32 v[100:101], v[100:101], v[178:179]
	s_waitcnt vmcnt(1)
	v_pk_add_f32 v[134:135], v[134:135], v[98:99]
	v_pk_add_f32 v[138:139], v[138:139], v[96:97]
	global_load_dwordx4 v[96:99], v[144:145], off nt
	global_load_dwordx4 v[186:189], v[142:143], off offset:16 nt
	v_lshl_add_u64 v[142:143], v[120:121], 0, s[64:65]
	s_waitcnt vmcnt(2)
	v_pk_add_f32 v[102:103], v[102:103], v[184:185]
	v_pk_add_f32 v[100:101], v[100:101], v[182:183]
	s_waitcnt vmcnt(1)
	v_pk_add_f32 v[134:135], v[134:135], v[98:99]
	v_pk_add_f32 v[138:139], v[138:139], v[96:97]
	global_load_dwordx4 v[96:99], v[148:149], off nt
	global_load_dwordx4 v[190:193], v[142:143], off offset:16 nt
	v_lshl_add_u64 v[142:143], v[120:121], 0, s[68:69]
	s_waitcnt vmcnt(2)
	v_pk_add_f32 v[102:103], v[102:103], v[188:189]
	v_pk_add_f32 v[100:101], v[100:101], v[186:187]
	s_waitcnt vmcnt(1)
	v_pk_add_f32 v[134:135], v[134:135], v[98:99]
	v_pk_add_f32 v[138:139], v[138:139], v[96:97]
	global_load_dwordx4 v[96:99], v[152:153], off nt
	global_load_dwordx4 v[194:197], v[142:143], off offset:16 nt
	global_load_dwordx4 v[124:127], v[120:121], off offset:2064 nt
	global_load_dwordx4 v[178:181], v[120:121], off offset:2048 nt
	global_load_dwordx4 v[182:185], v[122:123], off offset:2048 nt
	s_nop 0
	global_load_dwordx4 v[128:131], v[128:129], off offset:16 nt
	s_waitcnt vmcnt(6)
	v_pk_add_f32 v[102:103], v[102:103], v[192:193]
	v_pk_add_f32 v[100:101], v[100:101], v[190:191]
	s_waitcnt vmcnt(5)
	v_pk_add_f32 v[98:99], v[134:135], v[98:99]
	v_lshl_add_u64 v[134:135], v[120:121], 0, s[74:75]
	v_pk_add_f32 v[96:97], v[138:139], v[96:97]
	s_waitcnt vmcnt(1)
	v_pk_add_f32 v[122:123], v[180:181], v[184:185]
	v_pk_add_f32 v[138:139], v[178:179], v[182:183]
	global_load_dwordx4 v[178:181], v[132:133], off offset:2048 nt
	s_nop 0
	global_load_dwordx4 v[132:135], v[134:135], off offset:16 nt
	s_waitcnt vmcnt(2)
	v_pk_add_f32 v[126:127], v[126:127], v[130:131]
	v_pk_add_f32 v[124:125], v[124:125], v[128:129]
	v_pk_add_f32 v[102:103], v[102:103], v[196:197]
	v_pk_add_f32 v[100:101], v[100:101], v[194:195]
	s_waitcnt vmcnt(1)
	v_pk_add_f32 v[142:143], v[138:139], v[178:179]
	v_lshl_add_u64 v[138:139], v[120:121], 0, s[76:77]
	v_pk_add_f32 v[122:123], v[122:123], v[180:181]
	global_load_dwordx4 v[178:181], v[136:137], off offset:2048 nt
	s_nop 0
	global_load_dwordx4 v[136:139], v[138:139], off offset:16 nt
	s_waitcnt vmcnt(2)
	v_pk_add_f32 v[126:127], v[126:127], v[134:135]
	v_pk_add_f32 v[124:125], v[124:125], v[132:133]
	s_waitcnt vmcnt(1)
	v_pk_add_f32 v[146:147], v[142:143], v[178:179]
	v_lshl_add_u64 v[142:143], v[120:121], 0, s[94:95]
	v_pk_add_f32 v[122:123], v[122:123], v[180:181]
	global_load_dwordx4 v[178:181], v[140:141], off offset:2048 nt
	s_nop 0
	global_load_dwordx4 v[140:143], v[142:143], off offset:16 nt
	s_waitcnt vmcnt(2)
	v_pk_add_f32 v[126:127], v[126:127], v[138:139]
	v_pk_add_f32 v[124:125], v[124:125], v[136:137]
	v_readlane_b32 s94, v255, 27
	v_readlane_b32 s95, v255, 28
	s_waitcnt vmcnt(1)
	v_pk_add_f32 v[150:151], v[146:147], v[178:179]
	v_lshl_add_u64 v[146:147], v[120:121], 0, s[16:17]
	v_pk_add_f32 v[122:123], v[122:123], v[180:181]
	global_load_dwordx4 v[178:181], v[144:145], off offset:2048 nt
	s_nop 0
	global_load_dwordx4 v[144:147], v[146:147], off offset:16 nt
	s_waitcnt vmcnt(2)
	v_pk_add_f32 v[126:127], v[126:127], v[142:143]
	v_pk_add_f32 v[124:125], v[124:125], v[140:141]
	s_waitcnt vmcnt(1)
	v_pk_add_f32 v[154:155], v[150:151], v[178:179]
	v_lshl_add_u64 v[150:151], v[120:121], 0, s[96:97]
	v_pk_add_f32 v[122:123], v[122:123], v[180:181]
	global_load_dwordx4 v[180:183], v[148:149], off offset:2048 nt
	s_nop 0
	global_load_dwordx4 v[148:151], v[150:151], off offset:16 nt
	s_waitcnt vmcnt(2)
	v_pk_add_f32 v[126:127], v[126:127], v[146:147]
	v_pk_add_f32 v[124:125], v[124:125], v[144:145]
	s_mov_b32 s96, s38
	s_waitcnt vmcnt(1)
	v_pk_add_f32 v[180:181], v[154:155], v[180:181]
	v_lshl_add_u64 v[154:155], v[120:121], 0, s[36:37]
	v_pk_add_f32 v[178:179], v[122:123], v[182:183]
	global_load_dwordx4 v[120:123], v[152:153], off offset:2048 nt
	s_nop 0
	global_load_dwordx4 v[152:155], v[154:155], off offset:16 nt
	s_waitcnt vmcnt(2)
	v_pk_add_f32 v[126:127], v[126:127], v[150:151]
	v_pk_add_f32 v[124:125], v[124:125], v[148:149]
	s_waitcnt vmcnt(1)
	v_pk_add_f32 v[122:123], v[178:179], v[122:123]
	v_pk_add_f32 v[120:121], v[180:181], v[120:121]
	s_waitcnt vmcnt(0)
	v_pk_add_f32 v[126:127], v[126:127], v[154:155]
	v_pk_add_f32 v[124:125], v[124:125], v[152:153]
